# v31 + nt hint on the once-read f32 weight loads of the next-layer weight conversion that idle workgroups run during the WO/DOWN GEMM phases
# speedup vs baseline: 1.0220x; 1.0123x over previous
.LBB0_1022:
	s_ashr_i32 s11, s10, 31
	s_lshr_b32 s11, s11, 27
	s_add_i32 s11, s10, s11
	s_ashr_i32 s11, s11, 5
	s_lshl_b32 s14, s11, 6
	s_lshl_b32 s11, s11, 10
	s_andn2_b64 vcc, exec, s[6:7]
	s_sub_i32 s11, 0, s11
	s_cbranch_vccnz .LBB0_1024
	s_add_i32 s18, s9, s11
	v_or_b32_e32 v18, s14, v20
	s_ashr_i32 s19, s18, 31
	v_ashrrev_i32_e32 v19, 31, v18
	v_or_b32_e32 v14, 8, v18
	v_or_b32_e32 v26, 16, v18
	v_lshl_add_u64 v[46:47], s[18:19], 2, v[2:3]
	v_lshlrev_b64 v[6:7], 12, v[18:19]
	v_ashrrev_i32_e32 v15, 31, v14
	v_ashrrev_i32_e32 v27, 31, v26
	v_lshl_add_u64 v[6:7], v[46:47], 0, v[6:7]
	v_lshlrev_b64 v[14:15], 12, v[14:15]
	v_lshlrev_b64 v[26:27], 12, v[26:27]
	v_or_b32_e32 v30, 24, v18
	global_load_dwordx4 v[6:9], v[6:7], off nt
	v_lshl_add_u64 v[14:15], v[46:47], 0, v[14:15]
	v_lshl_add_u64 v[26:27], v[46:47], 0, v[26:27]
	v_ashrrev_i32_e32 v31, 31, v30
	v_or_b32_e32 v34, 32, v18
	global_load_dwordx4 v[14:17], v[14:15], off nt
	v_lshlrev_b64 v[30:31], 12, v[30:31]
	global_load_dwordx4 v[26:29], v[26:27], off nt
	v_ashrrev_i32_e32 v35, 31, v34
	v_lshl_add_u64 v[30:31], v[46:47], 0, v[30:31]
	v_lshlrev_b64 v[34:35], 12, v[34:35]
	v_or_b32_e32 v38, 40, v18
	global_load_dwordx4 v[30:33], v[30:31], off nt
	v_lshl_add_u64 v[34:35], v[46:47], 0, v[34:35]
	v_ashrrev_i32_e32 v39, 31, v38
	global_load_dwordx4 v[34:37], v[34:35], off nt
	v_lshlrev_b64 v[38:39], 12, v[38:39]
	v_or_b32_e32 v42, 48, v18
	v_lshl_add_u64 v[38:39], v[46:47], 0, v[38:39]
	v_ashrrev_i32_e32 v43, 31, v42
	global_load_dwordx4 v[38:41], v[38:39], off nt
	v_lshlrev_b64 v[42:43], 12, v[42:43]
	v_or_b32_e32 v18, 56, v18
	v_lshl_add_u64 v[42:43], v[46:47], 0, v[42:43]
	v_ashrrev_i32_e32 v19, 31, v18
	global_load_dwordx4 v[42:45], v[42:43], off nt
	v_lshlrev_b64 v[18:19], 12, v[18:19]
	v_lshl_add_u64 v[18:19], v[46:47], 0, v[18:19]
	global_load_dwordx4 v[46:49], v[18:19], off nt
	v_add_u32_e32 v0, v21, v23
	s_ashr_i32 s15, s14, 31
	s_waitcnt vmcnt(7)
	ds_write2_b32 v22, v6, v7 offset1:1
	ds_write2_b32 v22, v8, v9 offset0:2 offset1:3
	v_add_u32_e32 v6, 0x420, v0
	s_waitcnt vmcnt(6)
	ds_write2_b32 v0, v14, v15 offset1:1
	ds_write2_b32 v0, v16, v17 offset0:2 offset1:3
	s_waitcnt vmcnt(5)
	ds_write2_b32 v6, v26, v27 offset1:1
	v_add_u32_e32 v6, 0x428, v0
	ds_write2_b32 v6, v28, v29 offset1:1
	v_add_u32_e32 v6, 0x840, v0
	v_add_u32_e32 v0, 0x848, v0
	s_waitcnt vmcnt(4)
	ds_write2_b32 v0, v32, v33 offset1:1
	v_add_u32_e32 v0, 0x1080, v22
	ds_write2_b32 v6, v30, v31 offset1:1
	s_waitcnt vmcnt(3)
	ds_write2_b32 v0, v34, v35 offset1:1
	v_add_u32_e32 v0, 0x1088, v22
	ds_write2_b32 v0, v36, v37 offset1:1
	v_add_u32_e32 v0, 0x14a0, v22
	v_lshl_add_u64 v[6:7], s[14:15], 1, v[4:5]
	s_waitcnt vmcnt(2)
	ds_write2_b32 v0, v38, v39 offset1:1
	v_add_u32_e32 v0, 0x14a8, v22
	ds_write2_b32 v0, v40, v41 offset1:1
	v_add_u32_e32 v0, 0x18c0, v22
	v_add_u32_e32 v38, s18, v20
	s_waitcnt vmcnt(1)
	ds_write2_b32 v0, v42, v43 offset1:1
	v_add_u32_e32 v0, 0x18c8, v22
	ds_write2_b32 v0, v44, v45 offset1:1
	v_add_u32_e32 v0, 0x1ce0, v22
	s_waitcnt vmcnt(0)
	ds_write2_b32 v0, v46, v47 offset1:1
	v_add_u32_e32 v0, 0x1ce8, v22
	ds_write2_b32 v0, v48, v49 offset1:1
	s_waitcnt lgkmcnt(0)
	ds_read2_b32 v[8:9], v24 offset0:33 offset1:41
	ds_read2_b32 v[18:19], v24 offset1:8
	ds_read2_b32 v[26:27], v24 offset0:66 offset1:74
	ds_read2_b32 v[28:29], v24 offset0:99 offset1:107
	ds_read2_b32 v[30:31], v24 offset0:132 offset1:140
	ds_read2_b32 v[32:33], v24 offset0:165 offset1:173
	ds_read2_b32 v[34:35], v24 offset0:198 offset1:206
	ds_read2_b32 v[36:37], v24 offset0:231 offset1:239
	v_ashrrev_i32_e32 v39, 31, v38
	v_lshlrev_b64 v[40:41], 13, v[38:39]
	s_waitcnt lgkmcnt(6)
	v_cvt_pk_bf16_f32 v14, v18, v8
	s_waitcnt lgkmcnt(4)
	v_cvt_pk_bf16_f32 v15, v26, v28
	s_waitcnt lgkmcnt(2)
	v_cvt_pk_bf16_f32 v16, v30, v32
	s_waitcnt lgkmcnt(0)
	v_cvt_pk_bf16_f32 v17, v34, v36
	v_lshl_add_u64 v[40:41], v[6:7], 0, v[40:41]
	v_add_u32_e32 v8, 8, v38
	global_store_dwordx4 v[40:41], v[14:17], off
	v_add_u32_e32 v40, 16, v38
	v_ashrrev_i32_e32 v41, 31, v40
	v_cvt_pk_bf16_f32 v14, v19, v9
	v_ashrrev_i32_e32 v9, 31, v8
	v_lshlrev_b64 v[8:9], 13, v[8:9]
	v_cvt_pk_bf16_f32 v15, v27, v29
	v_cvt_pk_bf16_f32 v16, v31, v33
	v_cvt_pk_bf16_f32 v17, v35, v37
	v_lshl_add_u64 v[8:9], v[6:7], 0, v[8:9]
	global_store_dwordx4 v[8:9], v[14:17], off
	ds_read2_b32 v[8:9], v24 offset0:49 offset1:57
	ds_read2_b32 v[18:19], v24 offset0:16 offset1:24
	ds_read2_b32 v[26:27], v24 offset0:82 offset1:90
	ds_read2_b32 v[28:29], v24 offset0:115 offset1:123
	ds_read2_b32 v[30:31], v24 offset0:148 offset1:156
	ds_read2_b32 v[32:33], v24 offset0:181 offset1:189
	ds_read2_b32 v[34:35], v24 offset0:214 offset1:222
	ds_read2_b32 v[36:37], v24 offset0:247 offset1:255
	v_lshlrev_b64 v[40:41], 13, v[40:41]
	s_waitcnt lgkmcnt(6)
	v_cvt_pk_bf16_f32 v14, v18, v8
	s_waitcnt lgkmcnt(4)
	v_cvt_pk_bf16_f32 v15, v26, v28
	s_waitcnt lgkmcnt(2)
	v_cvt_pk_bf16_f32 v16, v30, v32
	s_waitcnt lgkmcnt(0)
	v_cvt_pk_bf16_f32 v17, v34, v36
	v_lshl_add_u64 v[40:41], v[6:7], 0, v[40:41]
	v_add_u32_e32 v8, 24, v38
	global_store_dwordx4 v[40:41], v[14:17], off
	s_nop 1
	v_cvt_pk_bf16_f32 v14, v19, v9
	v_ashrrev_i32_e32 v9, 31, v8
	v_lshlrev_b64 v[8:9], 13, v[8:9]
	v_cvt_pk_bf16_f32 v15, v27, v29
	v_cvt_pk_bf16_f32 v16, v31, v33
	v_cvt_pk_bf16_f32 v17, v35, v37
	v_lshl_add_u64 v[6:7], v[6:7], 0, v[8:9]
	global_store_dwordx4 v[6:7], v[14:17], off
	s_waitcnt lgkmcnt(0)
	s_cbranch_execnz .LBB0_1021
	s_branch .LBB0_1020

.LBB0_1030:
	s_mul_hi_i32 s11, s10, 0x2aaaaaab
	s_lshr_b32 s12, s11, 31
	s_ashr_i32 s11, s11, 3
	s_add_i32 s11, s11, s12
	s_lshl_b32 s18, s11, 6
	s_andn2_b64 vcc, exec, s[14:15]
	s_mulk_i32 s11, 0xfa00
	s_cbranch_vccnz .LBB0_1032
	s_add_i32 s24, s9, s11
	v_or_b32_e32 v0, s18, v20
	s_ashr_i32 s25, s24, 31
	v_lshl_add_u64 v[18:19], s[24:25], 2, v[2:3]
	v_or_b32_e32 v11, 8, v0
	v_mad_i64_i32 v[6:7], s[12:13], v0, s76, v[18:19]
	v_mad_i64_i32 v[14:15], s[12:13], v11, s76, v[18:19]
	v_or_b32_e32 v11, 16, v0
	global_load_dwordx4 v[6:9], v[6:7], off nt
	v_mad_i64_i32 v[26:27], s[12:13], v11, s76, v[18:19]
	global_load_dwordx4 v[14:17], v[14:15], off nt
	v_or_b32_e32 v11, 24, v0
	global_load_dwordx4 v[26:29], v[26:27], off nt
	v_mad_i64_i32 v[30:31], s[12:13], v11, s76, v[18:19]
	v_or_b32_e32 v11, 32, v0
	global_load_dwordx4 v[30:33], v[30:31], off nt
	v_mad_i64_i32 v[34:35], s[12:13], v11, s76, v[18:19]
	global_load_dwordx4 v[34:37], v[34:35], off nt
	v_or_b32_e32 v11, 40, v0
	v_mad_i64_i32 v[38:39], s[12:13], v11, s76, v[18:19]
	global_load_dwordx4 v[38:41], v[38:39], off nt
	v_or_b32_e32 v11, 48, v0
	v_mad_i64_i32 v[42:43], s[12:13], v11, s76, v[18:19]
	global_load_dwordx4 v[42:45], v[42:43], off nt
	v_or_b32_e32 v0, 56, v0
	v_mad_i64_i32 v[18:19], s[12:13], v0, s76, v[18:19]
	global_load_dwordx4 v[46:49], v[18:19], off nt
	v_add_u32_e32 v0, v21, v23
	s_ashr_i32 s19, s18, 31
	s_waitcnt vmcnt(7)
	ds_write2_b32 v22, v6, v7 offset1:1
	ds_write2_b32 v22, v8, v9 offset0:2 offset1:3
	v_add_u32_e32 v6, 0x420, v0
	s_waitcnt vmcnt(6)
	ds_write2_b32 v0, v14, v15 offset1:1
	ds_write2_b32 v0, v16, v17 offset0:2 offset1:3
	v_add_u32_e32 v8, s24, v20
	s_waitcnt vmcnt(5)
	ds_write2_b32 v6, v26, v27 offset1:1
	v_add_u32_e32 v6, 0x428, v0
	ds_write2_b32 v6, v28, v29 offset1:1
	v_add_u32_e32 v6, 0x840, v0
	v_add_u32_e32 v0, 0x848, v0
	s_waitcnt vmcnt(4)
	ds_write2_b32 v0, v32, v33 offset1:1
	v_add_u32_e32 v0, 0x1080, v22
	s_waitcnt vmcnt(3)
	ds_write2_b32 v0, v34, v35 offset1:1
	v_add_u32_e32 v0, 0x1088, v22
	ds_write2_b32 v0, v36, v37 offset1:1
	v_add_u32_e32 v0, 0x14a0, v22
	s_waitcnt vmcnt(2)
	ds_write2_b32 v0, v38, v39 offset1:1
	v_add_u32_e32 v0, 0x14a8, v22
	ds_write2_b32 v0, v40, v41 offset1:1
	v_add_u32_e32 v0, 0x18c0, v22
	s_waitcnt vmcnt(1)
	ds_write2_b32 v0, v42, v43 offset1:1
	v_add_u32_e32 v0, 0x18c8, v22
	ds_write2_b32 v0, v44, v45 offset1:1
	v_add_u32_e32 v0, 0x1ce0, v22
	s_waitcnt vmcnt(0)
	ds_write2_b32 v0, v46, v47 offset1:1
	v_add_u32_e32 v0, 0x1ce8, v22
	ds_write2_b32 v6, v30, v31 offset1:1
	ds_write2_b32 v0, v48, v49 offset1:1
	s_waitcnt lgkmcnt(0)
	ds_read2_b32 v[18:19], v24 offset0:33 offset1:41
	ds_read2_b32 v[26:27], v24 offset1:8
	ds_read2_b32 v[28:29], v24 offset0:66 offset1:74
	ds_read2_b32 v[30:31], v24 offset0:99 offset1:107
	ds_read2_b32 v[32:33], v24 offset0:132 offset1:140
	ds_read2_b32 v[34:35], v24 offset0:165 offset1:173
	ds_read2_b32 v[36:37], v24 offset0:198 offset1:206
	ds_read2_b32 v[38:39], v24 offset0:231 offset1:239
	v_ashrrev_i32_e32 v9, 31, v8
	v_lshl_add_u64 v[6:7], s[18:19], 1, v[4:5]
	v_lshlrev_b64 v[40:41], 11, v[8:9]
	s_waitcnt lgkmcnt(6)
	v_cvt_pk_bf16_f32 v14, v26, v18
	s_waitcnt lgkmcnt(4)
	v_cvt_pk_bf16_f32 v15, v28, v30
	s_waitcnt lgkmcnt(2)
	v_cvt_pk_bf16_f32 v16, v32, v34
	s_waitcnt lgkmcnt(0)
	v_cvt_pk_bf16_f32 v17, v36, v38
	v_lshl_add_u64 v[40:41], v[6:7], 0, v[40:41]
	v_add_u32_e32 v18, 8, v8
	global_store_dwordx4 v[40:41], v[14:17], off
	v_add_u32_e32 v40, 16, v8
	v_ashrrev_i32_e32 v41, 31, v40
	v_cvt_pk_bf16_f32 v14, v27, v19
	v_ashrrev_i32_e32 v19, 31, v18
	v_lshlrev_b64 v[18:19], 11, v[18:19]
	v_cvt_pk_bf16_f32 v15, v29, v31
	v_cvt_pk_bf16_f32 v16, v33, v35
	v_cvt_pk_bf16_f32 v17, v37, v39
	v_lshl_add_u64 v[18:19], v[6:7], 0, v[18:19]
	global_store_dwordx4 v[18:19], v[14:17], off
	ds_read2_b32 v[18:19], v24 offset0:49 offset1:57
	ds_read2_b32 v[26:27], v24 offset0:16 offset1:24
	ds_read2_b32 v[28:29], v24 offset0:82 offset1:90
	ds_read2_b32 v[30:31], v24 offset0:115 offset1:123
	ds_read2_b32 v[32:33], v24 offset0:148 offset1:156
	ds_read2_b32 v[34:35], v24 offset0:181 offset1:189
	ds_read2_b32 v[36:37], v24 offset0:214 offset1:222
	ds_read2_b32 v[38:39], v24 offset0:247 offset1:255
	v_add_u32_e32 v8, 24, v8
	v_lshlrev_b64 v[40:41], 11, v[40:41]
	v_ashrrev_i32_e32 v9, 31, v8
	s_waitcnt lgkmcnt(6)
	v_cvt_pk_bf16_f32 v14, v26, v18
	s_waitcnt lgkmcnt(4)
	v_cvt_pk_bf16_f32 v15, v28, v30
	s_waitcnt lgkmcnt(2)
	v_cvt_pk_bf16_f32 v16, v32, v34
	s_waitcnt lgkmcnt(0)
	v_cvt_pk_bf16_f32 v17, v36, v38
	v_lshl_add_u64 v[40:41], v[6:7], 0, v[40:41]
	v_lshlrev_b64 v[8:9], 11, v[8:9]
	global_store_dwordx4 v[40:41], v[14:17], off
	v_lshl_add_u64 v[6:7], v[6:7], 0, v[8:9]
	s_nop 0
	v_cvt_pk_bf16_f32 v14, v27, v19
	v_cvt_pk_bf16_f32 v15, v29, v31
	v_cvt_pk_bf16_f32 v16, v33, v35
	v_cvt_pk_bf16_f32 v17, v37, v39
	global_store_dwordx4 v[6:7], v[14:17], off
	s_waitcnt lgkmcnt(0)
	s_cbranch_execnz .LBB0_1029
	s_branch .LBB0_1028

.LBB0_1039:
	s_ashr_i32 s11, s9, 31
	s_lshr_b32 s11, s11, 27
	s_add_i32 s11, s9, s11
	s_ashr_i32 s11, s11, 5
	s_lshl_b32 s18, s11, 6
	s_lshl_b32 s11, s11, 10
	s_andn2_b64 vcc, exec, s[14:15]
	s_sub_i32 s11, 0, s11
	s_cbranch_vccnz .LBB0_1041
	s_add_i32 s24, s10, s11
	v_or_b32_e32 v18, s18, v20
	s_ashr_i32 s25, s24, 31
	v_ashrrev_i32_e32 v19, 31, v18
	v_or_b32_e32 v14, 8, v18
	v_or_b32_e32 v26, 16, v18
	v_lshl_add_u64 v[46:47], s[24:25], 2, v[2:3]
	v_lshlrev_b64 v[6:7], 12, v[18:19]
	v_ashrrev_i32_e32 v15, 31, v14
	v_ashrrev_i32_e32 v27, 31, v26
	v_lshl_add_u64 v[6:7], v[46:47], 0, v[6:7]
	v_lshlrev_b64 v[14:15], 12, v[14:15]
	v_lshlrev_b64 v[26:27], 12, v[26:27]
	v_or_b32_e32 v30, 24, v18
	global_load_dwordx4 v[6:9], v[6:7], off nt
	v_lshl_add_u64 v[14:15], v[46:47], 0, v[14:15]
	v_lshl_add_u64 v[26:27], v[46:47], 0, v[26:27]
	v_ashrrev_i32_e32 v31, 31, v30
	v_or_b32_e32 v34, 32, v18
	global_load_dwordx4 v[14:17], v[14:15], off nt
	v_lshlrev_b64 v[30:31], 12, v[30:31]
	global_load_dwordx4 v[26:29], v[26:27], off nt
	v_ashrrev_i32_e32 v35, 31, v34
	v_lshl_add_u64 v[30:31], v[46:47], 0, v[30:31]
	v_lshlrev_b64 v[34:35], 12, v[34:35]
	v_or_b32_e32 v38, 40, v18
	global_load_dwordx4 v[30:33], v[30:31], off nt
	v_lshl_add_u64 v[34:35], v[46:47], 0, v[34:35]
	v_ashrrev_i32_e32 v39, 31, v38
	global_load_dwordx4 v[34:37], v[34:35], off nt
	v_lshlrev_b64 v[38:39], 12, v[38:39]
	v_or_b32_e32 v42, 48, v18
	v_lshl_add_u64 v[38:39], v[46:47], 0, v[38:39]
	v_ashrrev_i32_e32 v43, 31, v42
	global_load_dwordx4 v[38:41], v[38:39], off nt
	v_lshlrev_b64 v[42:43], 12, v[42:43]
	v_or_b32_e32 v18, 56, v18
	v_lshl_add_u64 v[42:43], v[46:47], 0, v[42:43]
	v_ashrrev_i32_e32 v19, 31, v18
	global_load_dwordx4 v[42:45], v[42:43], off nt
	v_lshlrev_b64 v[18:19], 12, v[18:19]
	v_lshl_add_u64 v[18:19], v[46:47], 0, v[18:19]
	global_load_dwordx4 v[46:49], v[18:19], off nt
	v_add_u32_e32 v0, v21, v23
	s_ashr_i32 s19, s18, 31
	s_waitcnt vmcnt(7)
	ds_write2_b32 v22, v6, v7 offset1:1
	ds_write2_b32 v22, v8, v9 offset0:2 offset1:3
	v_add_u32_e32 v6, 0x420, v0
	s_waitcnt vmcnt(6)
	ds_write2_b32 v0, v14, v15 offset1:1
	ds_write2_b32 v0, v16, v17 offset0:2 offset1:3
	s_waitcnt vmcnt(5)
	ds_write2_b32 v6, v26, v27 offset1:1
	v_add_u32_e32 v6, 0x428, v0
	ds_write2_b32 v6, v28, v29 offset1:1
	v_add_u32_e32 v6, 0x840, v0
	v_add_u32_e32 v0, 0x848, v0
	s_waitcnt vmcnt(4)
	ds_write2_b32 v0, v32, v33 offset1:1
	v_add_u32_e32 v0, 0x1080, v22
	ds_write2_b32 v6, v30, v31 offset1:1
	s_waitcnt vmcnt(3)
	ds_write2_b32 v0, v34, v35 offset1:1
	v_add_u32_e32 v0, 0x1088, v22
	ds_write2_b32 v0, v36, v37 offset1:1
	v_add_u32_e32 v0, 0x14a0, v22
	v_lshl_add_u64 v[6:7], s[18:19], 1, v[4:5]
	s_waitcnt vmcnt(2)
	ds_write2_b32 v0, v38, v39 offset1:1
	v_add_u32_e32 v0, 0x14a8, v22
	ds_write2_b32 v0, v40, v41 offset1:1
	v_add_u32_e32 v0, 0x18c0, v22
	v_add_u32_e32 v38, s24, v20
	s_waitcnt vmcnt(1)
	ds_write2_b32 v0, v42, v43 offset1:1
	v_add_u32_e32 v0, 0x18c8, v22
	ds_write2_b32 v0, v44, v45 offset1:1
	v_add_u32_e32 v0, 0x1ce0, v22
	s_waitcnt vmcnt(0)
	ds_write2_b32 v0, v46, v47 offset1:1
	v_add_u32_e32 v0, 0x1ce8, v22
	ds_write2_b32 v0, v48, v49 offset1:1
	s_waitcnt lgkmcnt(0)
	ds_read2_b32 v[8:9], v24 offset0:33 offset1:41
	ds_read2_b32 v[18:19], v24 offset1:8
	ds_read2_b32 v[26:27], v24 offset0:66 offset1:74
	ds_read2_b32 v[28:29], v24 offset0:99 offset1:107
	ds_read2_b32 v[30:31], v24 offset0:132 offset1:140
	ds_read2_b32 v[32:33], v24 offset0:165 offset1:173
	ds_read2_b32 v[34:35], v24 offset0:198 offset1:206
	ds_read2_b32 v[36:37], v24 offset0:231 offset1:239
	v_ashrrev_i32_e32 v39, 31, v38
	v_lshlrev_b64 v[40:41], 11, v[38:39]
	s_waitcnt lgkmcnt(6)
	v_cvt_pk_bf16_f32 v14, v18, v8
	s_waitcnt lgkmcnt(4)
	v_cvt_pk_bf16_f32 v15, v26, v28
	s_waitcnt lgkmcnt(2)
	v_cvt_pk_bf16_f32 v16, v30, v32
	s_waitcnt lgkmcnt(0)
	v_cvt_pk_bf16_f32 v17, v34, v36
	v_lshl_add_u64 v[40:41], v[6:7], 0, v[40:41]
	v_add_u32_e32 v8, 8, v38
	global_store_dwordx4 v[40:41], v[14:17], off
	v_add_u32_e32 v40, 16, v38
	v_ashrrev_i32_e32 v41, 31, v40
	v_cvt_pk_bf16_f32 v14, v19, v9
	v_ashrrev_i32_e32 v9, 31, v8
	v_lshlrev_b64 v[8:9], 11, v[8:9]
	v_cvt_pk_bf16_f32 v15, v27, v29
	v_cvt_pk_bf16_f32 v16, v31, v33
	v_cvt_pk_bf16_f32 v17, v35, v37
	v_lshl_add_u64 v[8:9], v[6:7], 0, v[8:9]
	global_store_dwordx4 v[8:9], v[14:17], off
	ds_read2_b32 v[8:9], v24 offset0:49 offset1:57
	ds_read2_b32 v[18:19], v24 offset0:16 offset1:24
	ds_read2_b32 v[26:27], v24 offset0:82 offset1:90
	ds_read2_b32 v[28:29], v24 offset0:115 offset1:123
	ds_read2_b32 v[30:31], v24 offset0:148 offset1:156
	ds_read2_b32 v[32:33], v24 offset0:181 offset1:189
	ds_read2_b32 v[34:35], v24 offset0:214 offset1:222
	ds_read2_b32 v[36:37], v24 offset0:247 offset1:255
	v_lshlrev_b64 v[40:41], 11, v[40:41]
	s_waitcnt lgkmcnt(6)
	v_cvt_pk_bf16_f32 v14, v18, v8
	s_waitcnt lgkmcnt(4)
	v_cvt_pk_bf16_f32 v15, v26, v28
	s_waitcnt lgkmcnt(2)
	v_cvt_pk_bf16_f32 v16, v30, v32
	s_waitcnt lgkmcnt(0)
	v_cvt_pk_bf16_f32 v17, v34, v36
	v_lshl_add_u64 v[40:41], v[6:7], 0, v[40:41]
	v_add_u32_e32 v8, 24, v38
	global_store_dwordx4 v[40:41], v[14:17], off
	s_nop 1
	v_cvt_pk_bf16_f32 v14, v19, v9
	v_ashrrev_i32_e32 v9, 31, v8
	v_lshlrev_b64 v[8:9], 11, v[8:9]
	v_cvt_pk_bf16_f32 v15, v27, v29
	v_cvt_pk_bf16_f32 v16, v31, v33
	v_cvt_pk_bf16_f32 v17, v35, v37
	v_lshl_add_u64 v[6:7], v[6:7], 0, v[8:9]
	global_store_dwordx4 v[6:7], v[14:17], off
	s_waitcnt lgkmcnt(0)
	s_cbranch_execnz .LBB0_1038
	s_branch .LBB0_1037

.LBB0_1050:
	s_ashr_i32 s12, s11, 31
	s_lshr_b32 s12, s12, 27
	s_add_i32 s12, s11, s12
	s_ashr_i32 s12, s12, 5
	s_lshl_b32 s18, s12, 6
	s_lshl_b32 s12, s12, 10
	s_andn2_b64 vcc, exec, s[14:15]
	s_sub_i32 s12, 0, s12
	s_cbranch_vccnz .LBB0_1052
	s_add_i32 s24, s10, s12
	v_or_b32_e32 v14, s18, v20
	s_ashr_i32 s25, s24, 31
	v_ashrrev_i32_e32 v15, 31, v14
	v_lshl_add_u64 v[18:19], s[24:25], 2, v[4:5]
	v_lshlrev_b64 v[6:7], 12, v[14:15]
	v_or_b32_e32 v26, 8, v14
	v_or_b32_e32 v30, 16, v14
	v_lshl_add_u64 v[6:7], v[18:19], 0, v[6:7]
	v_ashrrev_i32_e32 v27, 31, v26
	v_ashrrev_i32_e32 v31, 31, v30
	global_load_dwordx4 v[6:9], v[6:7], off nt
	v_lshlrev_b64 v[26:27], 12, v[26:27]
	v_lshlrev_b64 v[30:31], 12, v[30:31]
	v_or_b32_e32 v34, 24, v14
	v_lshl_add_u64 v[26:27], v[18:19], 0, v[26:27]
	v_lshl_add_u64 v[30:31], v[18:19], 0, v[30:31]
	v_ashrrev_i32_e32 v35, 31, v34
	v_or_b32_e32 v38, 32, v14
	global_load_dwordx4 v[26:29], v[26:27], off nt
	v_lshlrev_b64 v[34:35], 12, v[34:35]
	global_load_dwordx4 v[30:33], v[30:31], off nt
	v_ashrrev_i32_e32 v39, 31, v38
	v_lshl_add_u64 v[34:35], v[18:19], 0, v[34:35]
	v_lshlrev_b64 v[38:39], 12, v[38:39]
	v_or_b32_e32 v42, 40, v14
	global_load_dwordx4 v[34:37], v[34:35], off nt
	v_lshl_add_u64 v[38:39], v[18:19], 0, v[38:39]
	v_ashrrev_i32_e32 v43, 31, v42
	global_load_dwordx4 v[38:41], v[38:39], off nt
	v_lshlrev_b64 v[42:43], 12, v[42:43]
	v_or_b32_e32 v46, 48, v14
	v_lshl_add_u64 v[42:43], v[18:19], 0, v[42:43]
	v_ashrrev_i32_e32 v47, 31, v46
	global_load_dwordx4 v[42:45], v[42:43], off nt
	v_lshlrev_b64 v[46:47], 12, v[46:47]
	v_or_b32_e32 v14, 56, v14
	v_lshl_add_u64 v[46:47], v[18:19], 0, v[46:47]
	v_ashrrev_i32_e32 v15, 31, v14
	global_load_dwordx4 v[46:49], v[46:47], off nt
	v_lshlrev_b64 v[14:15], 12, v[14:15]
	v_lshl_add_u64 v[14:15], v[18:19], 0, v[14:15]
	global_load_dwordx4 v[50:53], v[14:15], off nt
	s_ashr_i32 s19, s18, 31
	s_waitcnt vmcnt(7)
	ds_write2_b32 v22, v6, v7 offset1:1
	ds_write2_b32 v22, v8, v9 offset0:2 offset1:3
	v_add_u32_e32 v6, v21, v23
	v_add_u32_e32 v7, 0x420, v6
	s_waitcnt vmcnt(6)
	ds_write2_b32 v6, v26, v27 offset1:1
	ds_write2_b32 v6, v28, v29 offset0:2 offset1:3
	s_waitcnt vmcnt(5)
	ds_write2_b32 v7, v30, v31 offset1:1
	v_add_u32_e32 v7, 0x428, v6
	ds_write2_b32 v7, v32, v33 offset1:1
	v_add_u32_e32 v7, 0x840, v6
	v_add_u32_e32 v6, 0x848, v6
	s_waitcnt vmcnt(4)
	ds_write2_b32 v6, v36, v37 offset1:1
	v_add_u32_e32 v6, 0x1080, v22
	ds_write2_b32 v7, v34, v35 offset1:1
	s_waitcnt vmcnt(3)
	ds_write2_b32 v6, v38, v39 offset1:1
	v_add_u32_e32 v6, 0x1088, v22
	ds_write2_b32 v6, v40, v41 offset1:1
	v_add_u32_e32 v6, 0x14a0, v22
	v_add_u32_e32 v40, s24, v0
	s_waitcnt vmcnt(2)
	ds_write2_b32 v6, v42, v43 offset1:1
	v_add_u32_e32 v6, 0x14a8, v22
	ds_write2_b32 v6, v44, v45 offset1:1
	v_add_u32_e32 v6, 0x18c0, v22
	v_ashrrev_i32_e32 v41, 31, v40
	s_waitcnt vmcnt(1)
	ds_write2_b32 v6, v46, v47 offset1:1
	v_add_u32_e32 v6, 0x18c8, v22
	ds_write2_b32 v6, v48, v49 offset1:1
	v_add_u32_e32 v6, 0x1ce0, v22
	s_waitcnt vmcnt(0)
	ds_write2_b32 v6, v50, v51 offset1:1
	v_add_u32_e32 v6, 0x1ce8, v22
	ds_write2_b32 v6, v52, v53 offset1:1
	s_waitcnt lgkmcnt(0)
	ds_read2_b32 v[8:9], v24 offset0:33 offset1:41
	ds_read2_b32 v[14:15], v24 offset1:8
	ds_read2_b32 v[18:19], v24 offset0:66 offset1:74
	ds_read2_b32 v[30:31], v24 offset0:99 offset1:107
	ds_read2_b32 v[32:33], v24 offset0:132 offset1:140
	ds_read2_b32 v[34:35], v24 offset0:165 offset1:173
	ds_read2_b32 v[36:37], v24 offset0:198 offset1:206
	ds_read2_b32 v[38:39], v24 offset0:231 offset1:239
	v_lshl_add_u64 v[6:7], s[18:19], 1, v[16:17]
	v_lshlrev_b64 v[42:43], 12, v[40:41]
	s_waitcnt lgkmcnt(6)
	v_cvt_pk_bf16_f32 v26, v14, v8
	s_waitcnt lgkmcnt(4)
	v_cvt_pk_bf16_f32 v27, v18, v30
	s_waitcnt lgkmcnt(2)
	v_cvt_pk_bf16_f32 v28, v32, v34
	s_waitcnt lgkmcnt(0)
	v_cvt_pk_bf16_f32 v29, v36, v38
	v_lshl_add_u64 v[42:43], v[6:7], 0, v[42:43]
	v_add_u32_e32 v8, 8, v40
	global_store_dwordx4 v[42:43], v[26:29], off
	v_add_u32_e32 v42, 16, v40
	v_ashrrev_i32_e32 v43, 31, v42
	v_cvt_pk_bf16_f32 v26, v15, v9
	v_ashrrev_i32_e32 v9, 31, v8
	v_lshlrev_b64 v[8:9], 12, v[8:9]
	v_cvt_pk_bf16_f32 v27, v19, v31
	v_cvt_pk_bf16_f32 v28, v33, v35
	v_cvt_pk_bf16_f32 v29, v37, v39
	v_lshl_add_u64 v[8:9], v[6:7], 0, v[8:9]
	global_store_dwordx4 v[8:9], v[26:29], off
	ds_read2_b32 v[8:9], v24 offset0:49 offset1:57
	ds_read2_b32 v[14:15], v24 offset0:16 offset1:24
	ds_read2_b32 v[18:19], v24 offset0:82 offset1:90
	ds_read2_b32 v[30:31], v24 offset0:115 offset1:123
	ds_read2_b32 v[32:33], v24 offset0:148 offset1:156
	ds_read2_b32 v[34:35], v24 offset0:181 offset1:189
	ds_read2_b32 v[36:37], v24 offset0:214 offset1:222
	ds_read2_b32 v[38:39], v24 offset0:247 offset1:255
	v_lshlrev_b64 v[42:43], 12, v[42:43]
	s_waitcnt lgkmcnt(6)
	v_cvt_pk_bf16_f32 v26, v14, v8
	s_waitcnt lgkmcnt(4)
	v_cvt_pk_bf16_f32 v27, v18, v30
	s_waitcnt lgkmcnt(2)
	v_cvt_pk_bf16_f32 v28, v32, v34
	s_waitcnt lgkmcnt(0)
	v_cvt_pk_bf16_f32 v29, v36, v38
	v_lshl_add_u64 v[42:43], v[6:7], 0, v[42:43]
	v_add_u32_e32 v8, 24, v40
	global_store_dwordx4 v[42:43], v[26:29], off
	s_nop 1
	v_cvt_pk_bf16_f32 v26, v15, v9
	v_ashrrev_i32_e32 v9, 31, v8
	v_lshlrev_b64 v[8:9], 12, v[8:9]
	v_cvt_pk_bf16_f32 v27, v19, v31
	v_cvt_pk_bf16_f32 v28, v33, v35
	v_cvt_pk_bf16_f32 v29, v37, v39
	v_lshl_add_u64 v[6:7], v[6:7], 0, v[8:9]
	global_store_dwordx4 v[6:7], v[26:29], off
	s_waitcnt lgkmcnt(0)
	s_cbranch_execnz .LBB0_1049
	s_branch .LBB0_1048

.LBB0_1059:
	s_lshr_b32 s13, s11, 31
	s_add_i32 s13, s11, s13
	s_lshl_b32 s13, s13, 5
	s_and_b32 s36, s13, 0xffffffc0
	s_andn2_b64 vcc, exec, s[18:19]
	s_sub_i32 s13, 0, s36
	s_cbranch_vccnz .LBB0_1061
	s_add_i32 s38, s12, s13
	v_or_b32_e32 v8, s36, v20
	s_ashr_i32 s39, s38, 31
	v_ashrrev_i32_e32 v9, 31, v8
	v_or_b32_e32 v34, 8, v8
	v_or_b32_e32 v38, 16, v8
	v_lshl_add_u64 v[18:19], s[38:39], 2, v[2:3]
	v_lshlrev_b64 v[4:5], 8, v[8:9]
	v_ashrrev_i32_e32 v35, 31, v34
	v_ashrrev_i32_e32 v39, 31, v38
	v_lshl_add_u64 v[4:5], v[18:19], 0, v[4:5]
	v_lshlrev_b64 v[34:35], 8, v[34:35]
	v_lshlrev_b64 v[38:39], 8, v[38:39]
	v_or_b32_e32 v42, 24, v8
	global_load_dwordx4 v[4:7], v[4:5], off nt
	v_lshl_add_u64 v[34:35], v[18:19], 0, v[34:35]
	v_lshl_add_u64 v[38:39], v[18:19], 0, v[38:39]
	v_ashrrev_i32_e32 v43, 31, v42
	v_or_b32_e32 v46, 32, v8
	global_load_dwordx4 v[34:37], v[34:35], off nt
	v_lshlrev_b64 v[42:43], 8, v[42:43]
	global_load_dwordx4 v[38:41], v[38:39], off nt
	v_ashrrev_i32_e32 v47, 31, v46
	v_lshl_add_u64 v[42:43], v[18:19], 0, v[42:43]
	v_lshlrev_b64 v[46:47], 8, v[46:47]
	v_or_b32_e32 v50, 40, v8
	global_load_dwordx4 v[42:45], v[42:43], off nt
	v_lshl_add_u64 v[46:47], v[18:19], 0, v[46:47]
	v_ashrrev_i32_e32 v51, 31, v50
	global_load_dwordx4 v[46:49], v[46:47], off nt
	v_lshlrev_b64 v[50:51], 8, v[50:51]
	v_or_b32_e32 v54, 48, v8
	v_lshl_add_u64 v[50:51], v[18:19], 0, v[50:51]
	v_ashrrev_i32_e32 v55, 31, v54
	global_load_dwordx4 v[50:53], v[50:51], off nt
	v_lshlrev_b64 v[54:55], 8, v[54:55]
	v_or_b32_e32 v8, 56, v8
	v_lshl_add_u64 v[54:55], v[18:19], 0, v[54:55]
	v_ashrrev_i32_e32 v9, 31, v8
	global_load_dwordx4 v[54:57], v[54:55], off nt
	v_lshlrev_b64 v[8:9], 8, v[8:9]
	v_lshl_add_u64 v[8:9], v[18:19], 0, v[8:9]
	global_load_dwordx4 v[58:61], v[8:9], off nt
	v_add_u32_e32 v0, v21, v23
	v_add_u32_e32 v11, s38, v13
	s_ashr_i32 s37, s36, 31
	s_waitcnt vmcnt(7)
	ds_write2_b32 v22, v4, v5 offset1:1
	ds_write2_b32 v22, v6, v7 offset0:2 offset1:3
	v_add_u32_e32 v4, 0x420, v0
	s_waitcnt vmcnt(6)
	ds_write2_b32 v0, v34, v35 offset1:1
	ds_write2_b32 v0, v36, v37 offset0:2 offset1:3
	s_waitcnt vmcnt(5)
	ds_write2_b32 v4, v38, v39 offset1:1
	v_add_u32_e32 v4, 0x428, v0
	ds_write2_b32 v4, v40, v41 offset1:1
	v_add_u32_e32 v4, 0x840, v0
	v_add_u32_e32 v0, 0x848, v0
	s_waitcnt vmcnt(4)
	ds_write2_b32 v0, v44, v45 offset1:1
	v_add_u32_e32 v0, 0x1080, v22
	ds_write2_b32 v4, v42, v43 offset1:1
	s_waitcnt vmcnt(3)
	ds_write2_b32 v0, v46, v47 offset1:1
	v_add_u32_e32 v0, 0x1088, v22
	ds_write2_b32 v0, v48, v49 offset1:1
	v_add_u32_e32 v0, 0x14a0, v22
	v_lshl_add_u64 v[4:5], s[36:37], 1, v[16:17]
	s_waitcnt vmcnt(2)
	ds_write2_b32 v0, v50, v51 offset1:1
	v_add_u32_e32 v0, 0x14a8, v22
	ds_write2_b32 v0, v52, v53 offset1:1
	v_add_u32_e32 v0, 0x18c0, v22
	s_waitcnt vmcnt(1)
	ds_write2_b32 v0, v54, v55 offset1:1
	v_add_u32_e32 v0, 0x18c8, v22
	ds_write2_b32 v0, v56, v57 offset1:1
	v_add_u32_e32 v0, 0x1ce0, v22
	s_waitcnt vmcnt(0)
	ds_write2_b32 v0, v58, v59 offset1:1
	v_add_u32_e32 v0, 0x1ce8, v22
	ds_write2_b32 v0, v60, v61 offset1:1
	s_waitcnt lgkmcnt(0)
	ds_read2_b32 v[18:19], v24 offset0:33 offset1:41
	ds_read2_b32 v[34:35], v24 offset1:8
	ds_read2_b32 v[36:37], v24 offset0:66 offset1:74
	ds_read2_b32 v[38:39], v24 offset0:99 offset1:107
	ds_read2_b32 v[40:41], v24 offset0:132 offset1:140
	ds_read2_b32 v[42:43], v24 offset0:165 offset1:173
	ds_read2_b32 v[44:45], v24 offset0:198 offset1:206
	ds_read2_b32 v[46:47], v24 offset0:231 offset1:239
	v_add_u32_e32 v0, 0xc00, v11
	v_lshlrev_b64 v[48:49], 12, v[0:1]
	s_waitcnt lgkmcnt(6)
	v_cvt_pk_bf16_f32 v6, v34, v18
	s_waitcnt lgkmcnt(4)
	v_cvt_pk_bf16_f32 v7, v36, v38
	s_waitcnt lgkmcnt(2)
	v_cvt_pk_bf16_f32 v8, v40, v42
	s_waitcnt lgkmcnt(0)
	v_cvt_pk_bf16_f32 v9, v44, v46
	v_lshl_add_u64 v[48:49], v[4:5], 0, v[48:49]
	v_add_u32_e32 v0, 0xc08, v11
	global_store_dwordx4 v[48:49], v[6:9], off
	s_nop 1
	v_cvt_pk_bf16_f32 v6, v35, v19
	v_lshlrev_b64 v[18:19], 12, v[0:1]
	v_cvt_pk_bf16_f32 v7, v37, v39
	v_cvt_pk_bf16_f32 v8, v41, v43
	v_cvt_pk_bf16_f32 v9, v45, v47
	v_lshl_add_u64 v[18:19], v[4:5], 0, v[18:19]
	global_store_dwordx4 v[18:19], v[6:9], off
	ds_read2_b32 v[18:19], v24 offset0:49 offset1:57
	ds_read2_b32 v[34:35], v24 offset0:16 offset1:24
	ds_read2_b32 v[36:37], v24 offset0:82 offset1:90
	ds_read2_b32 v[38:39], v24 offset0:115 offset1:123
	ds_read2_b32 v[40:41], v24 offset0:148 offset1:156
	ds_read2_b32 v[42:43], v24 offset0:181 offset1:189
	ds_read2_b32 v[44:45], v24 offset0:214 offset1:222
	ds_read2_b32 v[46:47], v24 offset0:247 offset1:255
	v_add_u32_e32 v0, 0xc10, v11
	v_lshlrev_b64 v[48:49], 12, v[0:1]
	s_waitcnt lgkmcnt(6)
	v_cvt_pk_bf16_f32 v6, v34, v18
	s_waitcnt lgkmcnt(4)
	v_cvt_pk_bf16_f32 v7, v36, v38
	s_waitcnt lgkmcnt(2)
	v_cvt_pk_bf16_f32 v8, v40, v42
	s_waitcnt lgkmcnt(0)
	v_cvt_pk_bf16_f32 v9, v44, v46
	v_lshl_add_u64 v[48:49], v[4:5], 0, v[48:49]
	v_add_u32_e32 v0, 0xc18, v11
	global_store_dwordx4 v[48:49], v[6:9], off
	s_nop 1
	v_cvt_pk_bf16_f32 v6, v35, v19
	v_lshlrev_b64 v[18:19], 12, v[0:1]
	v_cvt_pk_bf16_f32 v7, v37, v39
	v_cvt_pk_bf16_f32 v8, v41, v43
	v_cvt_pk_bf16_f32 v9, v45, v47
	v_lshl_add_u64 v[4:5], v[4:5], 0, v[18:19]
	global_store_dwordx4 v[4:5], v[6:9], off
	s_waitcnt lgkmcnt(0)
	s_cbranch_execnz .LBB0_1058
	s_branch .LBB0_1057

.LBB0_1066:
	s_lshr_b32 s13, s11, 31
	s_add_i32 s13, s11, s13
	s_lshl_b32 s13, s13, 5
	s_and_b32 s34, s13, 0xffffffc0
	s_andn2_b64 vcc, exec, s[18:19]
	s_sub_i32 s13, 0, s34
	s_cbranch_vccnz .LBB0_1068
	s_add_i32 s36, s12, s13
	v_or_b32_e32 v58, s34, v20
	s_ashr_i32 s37, s36, 31
	v_ashrrev_i32_e32 v59, 31, v58
	v_lshl_add_u64 v[2:3], s[36:37], 2, v[18:19]
	v_lshlrev_b64 v[4:5], 8, v[58:59]
	v_lshl_add_u64 v[4:5], v[2:3], 0, v[4:5]
	global_load_dwordx4 v[34:37], v[4:5], off nt
	v_or_b32_e32 v4, 8, v58
	v_ashrrev_i32_e32 v5, 31, v4
	v_lshlrev_b64 v[4:5], 8, v[4:5]
	v_lshl_add_u64 v[4:5], v[2:3], 0, v[4:5]
	global_load_dwordx4 v[38:41], v[4:5], off nt
	v_or_b32_e32 v4, 16, v58
	v_ashrrev_i32_e32 v5, 31, v4
	v_lshlrev_b64 v[4:5], 8, v[4:5]
	v_lshl_add_u64 v[4:5], v[2:3], 0, v[4:5]
	global_load_dwordx4 v[42:45], v[4:5], off nt
	v_or_b32_e32 v4, 24, v58
	v_ashrrev_i32_e32 v5, 31, v4
	v_lshlrev_b64 v[4:5], 8, v[4:5]
	v_lshl_add_u64 v[4:5], v[2:3], 0, v[4:5]
	global_load_dwordx4 v[46:49], v[4:5], off nt
	v_or_b32_e32 v4, 32, v58
	v_ashrrev_i32_e32 v5, 31, v4
	v_lshlrev_b64 v[4:5], 8, v[4:5]
	v_lshl_add_u64 v[4:5], v[2:3], 0, v[4:5]
	global_load_dwordx4 v[50:53], v[4:5], off nt
	v_or_b32_e32 v4, 40, v58
	v_ashrrev_i32_e32 v5, 31, v4
	v_lshlrev_b64 v[4:5], 8, v[4:5]
	v_lshl_add_u64 v[4:5], v[2:3], 0, v[4:5]
	global_load_dwordx4 v[54:57], v[4:5], off nt
	v_or_b32_e32 v4, 48, v58
	v_ashrrev_i32_e32 v5, 31, v4
	v_lshlrev_b64 v[4:5], 8, v[4:5]
	v_lshl_add_u64 v[4:5], v[2:3], 0, v[4:5]
	global_load_dwordx4 v[6:9], v[4:5], off nt
	v_or_b32_e32 v4, 56, v58
	v_lshl_add_u64 v[58:59], v[58:59], 2, s[24:25]
	global_load_dword v0, v[58:59], off
	v_ashrrev_i32_e32 v5, 31, v4
	v_lshlrev_b64 v[4:5], 8, v[4:5]
	v_lshl_add_u64 v[2:3], v[2:3], 0, v[4:5]
	global_load_dwordx4 v[2:5], v[2:3], off nt
	v_add_u32_e32 v11, v21, v23
	s_ashr_i32 s35, s34, 31
	s_waitcnt vmcnt(1)
	v_pk_mul_f32 v[34:35], v[34:35], v[0:1] op_sel_hi:[1,0]
	v_pk_mul_f32 v[36:37], v[36:37], v[0:1] op_sel_hi:[1,0]
	ds_write2_b32 v22, v34, v35 offset1:1
	ds_write2_b32 v22, v36, v37 offset0:2 offset1:3
	v_or_b32_e32 v34, s34, v26
	v_ashrrev_i32_e32 v35, 31, v34
	v_lshl_add_u64 v[34:35], v[34:35], 2, s[24:25]
	global_load_dword v0, v[34:35], off
	s_waitcnt vmcnt(0)
	v_pk_mul_f32 v[34:35], v[40:41], v[0:1] op_sel_hi:[1,0]
	v_pk_mul_f32 v[36:37], v[38:39], v[0:1] op_sel_hi:[1,0]
	ds_write2_b32 v11, v36, v37 offset1:1
	ds_write2_b32 v11, v34, v35 offset0:2 offset1:3
	v_or_b32_e32 v34, s34, v27
	v_ashrrev_i32_e32 v35, 31, v34
	v_lshl_add_u64 v[34:35], v[34:35], 2, s[24:25]
	global_load_dword v0, v[34:35], off
	s_waitcnt vmcnt(0)
	v_pk_mul_f32 v[34:35], v[44:45], v[0:1] op_sel_hi:[1,0]
	v_pk_mul_f32 v[36:37], v[42:43], v[0:1] op_sel_hi:[1,0]
	v_add_u32_e32 v0, 0x420, v11
	ds_write2_b32 v0, v36, v37 offset1:1
	v_add_u32_e32 v0, 0x428, v11
	ds_write2_b32 v0, v34, v35 offset1:1
	v_or_b32_e32 v34, s34, v25
	v_ashrrev_i32_e32 v35, 31, v34
	v_lshl_add_u64 v[34:35], v[34:35], 2, s[24:25]
	global_load_dword v0, v[34:35], off
	s_waitcnt vmcnt(0)
	v_pk_mul_f32 v[34:35], v[48:49], v[0:1] op_sel_hi:[1,0]
	v_pk_mul_f32 v[36:37], v[46:47], v[0:1] op_sel_hi:[1,0]
	v_add_u32_e32 v0, 0x840, v11
	ds_write2_b32 v0, v36, v37 offset1:1
	v_add_u32_e32 v0, 0x848, v11
	ds_write2_b32 v0, v34, v35 offset1:1
	v_or_b32_e32 v34, s34, v28
	v_ashrrev_i32_e32 v35, 31, v34
	v_lshl_add_u64 v[34:35], v[34:35], 2, s[24:25]
	global_load_dword v0, v[34:35], off
	v_add_u32_e32 v11, v21, v29
	s_waitcnt vmcnt(0)
	v_pk_mul_f32 v[34:35], v[52:53], v[0:1] op_sel_hi:[1,0]
	v_pk_mul_f32 v[36:37], v[50:51], v[0:1] op_sel_hi:[1,0]
	ds_write2_b32 v11, v36, v37 offset1:1
	ds_write2_b32 v11, v34, v35 offset0:2 offset1:3
	v_or_b32_e32 v34, s34, v30
	v_ashrrev_i32_e32 v35, 31, v34
	v_lshl_add_u64 v[34:35], v[34:35], 2, s[24:25]
	global_load_dword v0, v[34:35], off
	s_waitcnt vmcnt(0)
	v_pk_mul_f32 v[34:35], v[56:57], v[0:1] op_sel_hi:[1,0]
	v_pk_mul_f32 v[36:37], v[54:55], v[0:1] op_sel_hi:[1,0]
	v_add_u32_e32 v0, 0x420, v11
	ds_write2_b32 v0, v36, v37 offset1:1
	v_add_u32_e32 v0, 0x428, v11
	ds_write2_b32 v0, v34, v35 offset1:1
	v_or_b32_e32 v34, s34, v31
	v_ashrrev_i32_e32 v35, 31, v34
	v_lshl_add_u64 v[34:35], v[34:35], 2, s[24:25]
	global_load_dword v0, v[34:35], off
	s_waitcnt vmcnt(0)
	v_pk_mul_f32 v[8:9], v[8:9], v[0:1] op_sel_hi:[1,0]
	v_pk_mul_f32 v[6:7], v[6:7], v[0:1] op_sel_hi:[1,0]
	v_add_u32_e32 v0, 0x840, v11
	ds_write2_b32 v0, v6, v7 offset1:1
	v_or_b32_e32 v6, s34, v32
	v_ashrrev_i32_e32 v7, 31, v6
	v_add_u32_e32 v0, 0x848, v11
	v_lshl_add_u64 v[6:7], v[6:7], 2, s[24:25]
	ds_write2_b32 v0, v8, v9 offset1:1
	global_load_dword v0, v[6:7], off
	v_lshl_add_u64 v[6:7], s[34:35], 1, v[14:15]
	s_waitcnt vmcnt(0)
	v_pk_mul_f32 v[4:5], v[4:5], v[0:1] op_sel_hi:[1,0]
	v_pk_mul_f32 v[2:3], v[2:3], v[0:1] op_sel_hi:[1,0]
	v_add_u32_e32 v0, 0xc60, v11
	ds_write2_b32 v0, v2, v3 offset1:1
	v_add_u32_e32 v0, 0xc68, v11
	ds_write2_b32 v0, v4, v5 offset1:1
	s_waitcnt lgkmcnt(0)
	ds_read2_b32 v[8:9], v24 offset0:33 offset1:41
	ds_read2_b32 v[34:35], v24 offset1:8
	ds_read2_b32 v[36:37], v24 offset0:66 offset1:74
	ds_read2_b32 v[38:39], v24 offset0:99 offset1:107
	ds_read2_b32 v[40:41], v24 offset0:132 offset1:140
	ds_read2_b32 v[42:43], v24 offset0:165 offset1:173
	ds_read2_b32 v[44:45], v24 offset0:198 offset1:206
	ds_read2_b32 v[46:47], v24 offset0:231 offset1:239
	v_add_u32_e32 v11, s36, v13
	v_add_u32_e32 v0, 0xc00, v11
	v_lshlrev_b64 v[48:49], 12, v[0:1]
	s_waitcnt lgkmcnt(6)
	v_cvt_pk_bf16_f32 v2, v34, v8
	s_waitcnt lgkmcnt(4)
	v_cvt_pk_bf16_f32 v3, v36, v38
	s_waitcnt lgkmcnt(2)
	v_cvt_pk_bf16_f32 v4, v40, v42
	s_waitcnt lgkmcnt(0)
	v_cvt_pk_bf16_f32 v5, v44, v46
	v_lshl_add_u64 v[48:49], v[6:7], 0, v[48:49]
	v_add_u32_e32 v0, 0xc08, v11
	global_store_dwordx4 v[48:49], v[2:5], off
	s_nop 1
	v_cvt_pk_bf16_f32 v2, v35, v9
	v_lshlrev_b64 v[8:9], 12, v[0:1]
	v_cvt_pk_bf16_f32 v3, v37, v39
	v_cvt_pk_bf16_f32 v4, v41, v43
	v_cvt_pk_bf16_f32 v5, v45, v47
	v_lshl_add_u64 v[8:9], v[6:7], 0, v[8:9]
	global_store_dwordx4 v[8:9], v[2:5], off
	ds_read2_b32 v[8:9], v24 offset0:49 offset1:57
	ds_read2_b32 v[34:35], v24 offset0:16 offset1:24
	ds_read2_b32 v[36:37], v24 offset0:82 offset1:90
	ds_read2_b32 v[38:39], v24 offset0:115 offset1:123
	ds_read2_b32 v[40:41], v24 offset0:148 offset1:156
	ds_read2_b32 v[42:43], v24 offset0:181 offset1:189
	ds_read2_b32 v[44:45], v24 offset0:214 offset1:222
	ds_read2_b32 v[46:47], v24 offset0:247 offset1:255
	v_add_u32_e32 v0, 0xc10, v11
	v_lshlrev_b64 v[48:49], 12, v[0:1]
	s_waitcnt lgkmcnt(6)
	v_cvt_pk_bf16_f32 v2, v34, v8
	s_waitcnt lgkmcnt(4)
	v_cvt_pk_bf16_f32 v3, v36, v38
	s_waitcnt lgkmcnt(2)
	v_cvt_pk_bf16_f32 v4, v40, v42
	s_waitcnt lgkmcnt(0)
	v_cvt_pk_bf16_f32 v5, v44, v46
	v_lshl_add_u64 v[48:49], v[6:7], 0, v[48:49]
	v_add_u32_e32 v0, 0xc18, v11
	global_store_dwordx4 v[48:49], v[2:5], off
	s_nop 1
	v_cvt_pk_bf16_f32 v2, v35, v9
	v_lshlrev_b64 v[8:9], 12, v[0:1]
	v_cvt_pk_bf16_f32 v3, v37, v39
	v_cvt_pk_bf16_f32 v4, v41, v43
	v_cvt_pk_bf16_f32 v5, v45, v47
	v_lshl_add_u64 v[6:7], v[6:7], 0, v[8:9]
	global_store_dwordx4 v[6:7], v[2:5], off
	s_waitcnt lgkmcnt(0)
	s_cbranch_execnz .LBB0_1065
	s_branch .LBB0_1064

.LBB0_1073:
	s_lshr_b32 s13, s11, 31
	s_add_i32 s13, s11, s13
	s_lshl_b32 s13, s13, 5
	s_and_b32 s38, s13, 0xffffffc0
	s_andn2_b64 vcc, exec, s[30:31]
	s_sub_i32 s13, 0, s38
	s_cbranch_vccnz .LBB0_1075
	s_add_i32 s42, s12, s13
	v_or_b32_e32 v8, s38, v20
	s_ashr_i32 s43, s42, 31
	v_ashrrev_i32_e32 v9, 31, v8
	v_or_b32_e32 v34, 8, v8
	v_or_b32_e32 v38, 16, v8
	v_lshl_add_u64 v[18:19], s[42:43], 2, v[2:3]
	v_lshlrev_b64 v[4:5], 8, v[8:9]
	v_ashrrev_i32_e32 v35, 31, v34
	v_ashrrev_i32_e32 v39, 31, v38
	v_lshl_add_u64 v[4:5], v[18:19], 0, v[4:5]
	v_lshlrev_b64 v[34:35], 8, v[34:35]
	v_lshlrev_b64 v[38:39], 8, v[38:39]
	v_or_b32_e32 v42, 24, v8
	global_load_dwordx4 v[4:7], v[4:5], off nt
	v_lshl_add_u64 v[34:35], v[18:19], 0, v[34:35]
	v_lshl_add_u64 v[38:39], v[18:19], 0, v[38:39]
	v_ashrrev_i32_e32 v43, 31, v42
	v_or_b32_e32 v46, 32, v8
	global_load_dwordx4 v[34:37], v[34:35], off nt
	v_lshlrev_b64 v[42:43], 8, v[42:43]
	global_load_dwordx4 v[38:41], v[38:39], off nt
	v_ashrrev_i32_e32 v47, 31, v46
	v_lshl_add_u64 v[42:43], v[18:19], 0, v[42:43]
	v_lshlrev_b64 v[46:47], 8, v[46:47]
	v_or_b32_e32 v50, 40, v8
	global_load_dwordx4 v[42:45], v[42:43], off nt
	v_lshl_add_u64 v[46:47], v[18:19], 0, v[46:47]
	v_ashrrev_i32_e32 v51, 31, v50
	global_load_dwordx4 v[46:49], v[46:47], off nt
	v_lshlrev_b64 v[50:51], 8, v[50:51]
	v_or_b32_e32 v54, 48, v8
	v_lshl_add_u64 v[50:51], v[18:19], 0, v[50:51]
	v_ashrrev_i32_e32 v55, 31, v54
	global_load_dwordx4 v[50:53], v[50:51], off nt
	v_lshlrev_b64 v[54:55], 8, v[54:55]
	v_or_b32_e32 v8, 56, v8
	v_lshl_add_u64 v[54:55], v[18:19], 0, v[54:55]
	v_ashrrev_i32_e32 v9, 31, v8
	global_load_dwordx4 v[54:57], v[54:55], off nt
	v_lshlrev_b64 v[8:9], 8, v[8:9]
	v_lshl_add_u64 v[8:9], v[18:19], 0, v[8:9]
	global_load_dwordx4 v[58:61], v[8:9], off nt
	v_add_u32_e32 v0, v21, v23
	v_add_u32_e32 v11, s42, v13
	s_ashr_i32 s39, s38, 31
	s_waitcnt vmcnt(7)
	ds_write2_b32 v22, v4, v5 offset1:1
	ds_write2_b32 v22, v6, v7 offset0:2 offset1:3
	v_add_u32_e32 v4, 0x420, v0
	s_waitcnt vmcnt(6)
	ds_write2_b32 v0, v34, v35 offset1:1
	ds_write2_b32 v0, v36, v37 offset0:2 offset1:3
	s_waitcnt vmcnt(5)
	ds_write2_b32 v4, v38, v39 offset1:1
	v_add_u32_e32 v4, 0x428, v0
	ds_write2_b32 v4, v40, v41 offset1:1
	v_add_u32_e32 v4, 0x840, v0
	v_add_u32_e32 v0, 0x848, v0
	s_waitcnt vmcnt(4)
	ds_write2_b32 v0, v44, v45 offset1:1
	v_add_u32_e32 v0, 0x1080, v22
	ds_write2_b32 v4, v42, v43 offset1:1
	s_waitcnt vmcnt(3)
	ds_write2_b32 v0, v46, v47 offset1:1
	v_add_u32_e32 v0, 0x1088, v22
	ds_write2_b32 v0, v48, v49 offset1:1
	v_add_u32_e32 v0, 0x14a0, v22
	v_lshl_add_u64 v[4:5], s[38:39], 1, v[16:17]
	s_waitcnt vmcnt(2)
	ds_write2_b32 v0, v50, v51 offset1:1
	v_add_u32_e32 v0, 0x14a8, v22
	ds_write2_b32 v0, v52, v53 offset1:1
	v_add_u32_e32 v0, 0x18c0, v22
	s_waitcnt vmcnt(1)
	ds_write2_b32 v0, v54, v55 offset1:1
	v_add_u32_e32 v0, 0x18c8, v22
	ds_write2_b32 v0, v56, v57 offset1:1
	v_add_u32_e32 v0, 0x1ce0, v22
	s_waitcnt vmcnt(0)
	ds_write2_b32 v0, v58, v59 offset1:1
	v_add_u32_e32 v0, 0x1ce8, v22
	ds_write2_b32 v0, v60, v61 offset1:1
	s_waitcnt lgkmcnt(0)
	ds_read2_b32 v[18:19], v24 offset0:33 offset1:41
	ds_read2_b32 v[34:35], v24 offset1:8
	ds_read2_b32 v[36:37], v24 offset0:66 offset1:74
	ds_read2_b32 v[38:39], v24 offset0:99 offset1:107
	ds_read2_b32 v[40:41], v24 offset0:132 offset1:140
	ds_read2_b32 v[42:43], v24 offset0:165 offset1:173
	ds_read2_b32 v[44:45], v24 offset0:198 offset1:206
	ds_read2_b32 v[46:47], v24 offset0:231 offset1:239
	v_add_u32_e32 v0, 0xc80, v11
	v_lshlrev_b64 v[48:49], 12, v[0:1]
	s_waitcnt lgkmcnt(6)
	v_cvt_pk_bf16_f32 v6, v34, v18
	s_waitcnt lgkmcnt(4)
	v_cvt_pk_bf16_f32 v7, v36, v38
	s_waitcnt lgkmcnt(2)
	v_cvt_pk_bf16_f32 v8, v40, v42
	s_waitcnt lgkmcnt(0)
	v_cvt_pk_bf16_f32 v9, v44, v46
	v_lshl_add_u64 v[48:49], v[4:5], 0, v[48:49]
	v_add_u32_e32 v0, 0xc88, v11
	global_store_dwordx4 v[48:49], v[6:9], off
	s_nop 1
	v_cvt_pk_bf16_f32 v6, v35, v19
	v_lshlrev_b64 v[18:19], 12, v[0:1]
	v_cvt_pk_bf16_f32 v7, v37, v39
	v_cvt_pk_bf16_f32 v8, v41, v43
	v_cvt_pk_bf16_f32 v9, v45, v47
	v_lshl_add_u64 v[18:19], v[4:5], 0, v[18:19]
	global_store_dwordx4 v[18:19], v[6:9], off
	ds_read2_b32 v[18:19], v24 offset0:49 offset1:57
	ds_read2_b32 v[34:35], v24 offset0:16 offset1:24
	ds_read2_b32 v[36:37], v24 offset0:82 offset1:90
	ds_read2_b32 v[38:39], v24 offset0:115 offset1:123
	ds_read2_b32 v[40:41], v24 offset0:148 offset1:156
	ds_read2_b32 v[42:43], v24 offset0:181 offset1:189
	ds_read2_b32 v[44:45], v24 offset0:214 offset1:222
	ds_read2_b32 v[46:47], v24 offset0:247 offset1:255
	v_add_u32_e32 v0, 0xc90, v11
	v_lshlrev_b64 v[48:49], 12, v[0:1]
	s_waitcnt lgkmcnt(6)
	v_cvt_pk_bf16_f32 v6, v34, v18
	s_waitcnt lgkmcnt(4)
	v_cvt_pk_bf16_f32 v7, v36, v38
	s_waitcnt lgkmcnt(2)
	v_cvt_pk_bf16_f32 v8, v40, v42
	s_waitcnt lgkmcnt(0)
	v_cvt_pk_bf16_f32 v9, v44, v46
	v_lshl_add_u64 v[48:49], v[4:5], 0, v[48:49]
	v_add_u32_e32 v0, 0xc98, v11
	global_store_dwordx4 v[48:49], v[6:9], off
	s_nop 1
	v_cvt_pk_bf16_f32 v6, v35, v19
	v_lshlrev_b64 v[18:19], 12, v[0:1]
	v_cvt_pk_bf16_f32 v7, v37, v39
	v_cvt_pk_bf16_f32 v8, v41, v43
	v_cvt_pk_bf16_f32 v9, v45, v47
	v_lshl_add_u64 v[4:5], v[4:5], 0, v[18:19]
	global_store_dwordx4 v[4:5], v[6:9], off
	s_waitcnt lgkmcnt(0)
	s_cbranch_execnz .LBB0_1072
	s_branch .LBB0_1071

.LBB0_1080:
	s_lshr_b32 s12, s10, 31
	s_add_i32 s12, s10, s12
	s_lshl_b32 s12, s12, 5
	s_and_b32 s34, s12, 0xffffffc0
	s_andn2_b64 vcc, exec, s[30:31]
	s_sub_i32 s12, 0, s34
	s_cbranch_vccnz .LBB0_1082
	s_add_i32 s36, s11, s12
	v_or_b32_e32 v58, s34, v20
	s_ashr_i32 s37, s36, 31
	v_ashrrev_i32_e32 v59, 31, v58
	v_lshl_add_u64 v[2:3], s[36:37], 2, v[18:19]
	v_lshlrev_b64 v[4:5], 8, v[58:59]
	v_lshl_add_u64 v[4:5], v[2:3], 0, v[4:5]
	global_load_dwordx4 v[34:37], v[4:5], off nt
	v_or_b32_e32 v4, 8, v58
	v_ashrrev_i32_e32 v5, 31, v4
	v_lshlrev_b64 v[4:5], 8, v[4:5]
	v_lshl_add_u64 v[4:5], v[2:3], 0, v[4:5]
	global_load_dwordx4 v[38:41], v[4:5], off nt
	v_or_b32_e32 v4, 16, v58
	v_ashrrev_i32_e32 v5, 31, v4
	v_lshlrev_b64 v[4:5], 8, v[4:5]
	v_lshl_add_u64 v[4:5], v[2:3], 0, v[4:5]
	global_load_dwordx4 v[42:45], v[4:5], off nt
	v_or_b32_e32 v4, 24, v58
	v_ashrrev_i32_e32 v5, 31, v4
	v_lshlrev_b64 v[4:5], 8, v[4:5]
	v_lshl_add_u64 v[4:5], v[2:3], 0, v[4:5]
	global_load_dwordx4 v[46:49], v[4:5], off nt
	v_or_b32_e32 v4, 32, v58
	v_ashrrev_i32_e32 v5, 31, v4
	v_lshlrev_b64 v[4:5], 8, v[4:5]
	v_lshl_add_u64 v[4:5], v[2:3], 0, v[4:5]
	global_load_dwordx4 v[50:53], v[4:5], off nt
	v_or_b32_e32 v4, 40, v58
	v_ashrrev_i32_e32 v5, 31, v4
	v_lshlrev_b64 v[4:5], 8, v[4:5]
	v_lshl_add_u64 v[4:5], v[2:3], 0, v[4:5]
	global_load_dwordx4 v[54:57], v[4:5], off nt
	v_or_b32_e32 v4, 48, v58
	v_ashrrev_i32_e32 v5, 31, v4
	v_lshlrev_b64 v[4:5], 8, v[4:5]
	v_lshl_add_u64 v[4:5], v[2:3], 0, v[4:5]
	global_load_dwordx4 v[6:9], v[4:5], off nt
	v_or_b32_e32 v4, 56, v58
	v_lshl_add_u64 v[58:59], v[58:59], 2, s[26:27]
	global_load_dword v0, v[58:59], off
	v_ashrrev_i32_e32 v5, 31, v4
	v_lshlrev_b64 v[4:5], 8, v[4:5]
	v_lshl_add_u64 v[2:3], v[2:3], 0, v[4:5]
	global_load_dwordx4 v[2:5], v[2:3], off nt
	v_add_u32_e32 v11, v21, v23
	s_ashr_i32 s35, s34, 31
	s_waitcnt vmcnt(1)
	v_pk_mul_f32 v[34:35], v[34:35], v[0:1] op_sel_hi:[1,0]
	v_pk_mul_f32 v[36:37], v[36:37], v[0:1] op_sel_hi:[1,0]
	ds_write2_b32 v22, v34, v35 offset1:1
	ds_write2_b32 v22, v36, v37 offset0:2 offset1:3
	v_or_b32_e32 v34, s34, v26
	v_ashrrev_i32_e32 v35, 31, v34
	v_lshl_add_u64 v[34:35], v[34:35], 2, s[26:27]
	global_load_dword v0, v[34:35], off
	s_waitcnt vmcnt(0)
	v_pk_mul_f32 v[34:35], v[40:41], v[0:1] op_sel_hi:[1,0]
	v_pk_mul_f32 v[36:37], v[38:39], v[0:1] op_sel_hi:[1,0]
	ds_write2_b32 v11, v36, v37 offset1:1
	ds_write2_b32 v11, v34, v35 offset0:2 offset1:3
	v_or_b32_e32 v34, s34, v27
	v_ashrrev_i32_e32 v35, 31, v34
	v_lshl_add_u64 v[34:35], v[34:35], 2, s[26:27]
	global_load_dword v0, v[34:35], off
	s_waitcnt vmcnt(0)
	v_pk_mul_f32 v[34:35], v[44:45], v[0:1] op_sel_hi:[1,0]
	v_pk_mul_f32 v[36:37], v[42:43], v[0:1] op_sel_hi:[1,0]
	v_add_u32_e32 v0, 0x420, v11
	ds_write2_b32 v0, v36, v37 offset1:1
	v_add_u32_e32 v0, 0x428, v11
	ds_write2_b32 v0, v34, v35 offset1:1
	v_or_b32_e32 v34, s34, v25
	v_ashrrev_i32_e32 v35, 31, v34
	v_lshl_add_u64 v[34:35], v[34:35], 2, s[26:27]
	global_load_dword v0, v[34:35], off
	s_waitcnt vmcnt(0)
	v_pk_mul_f32 v[34:35], v[48:49], v[0:1] op_sel_hi:[1,0]
	v_pk_mul_f32 v[36:37], v[46:47], v[0:1] op_sel_hi:[1,0]
	v_add_u32_e32 v0, 0x840, v11
	ds_write2_b32 v0, v36, v37 offset1:1
	v_add_u32_e32 v0, 0x848, v11
	ds_write2_b32 v0, v34, v35 offset1:1
	v_or_b32_e32 v34, s34, v28
	v_ashrrev_i32_e32 v35, 31, v34
	v_lshl_add_u64 v[34:35], v[34:35], 2, s[26:27]
	global_load_dword v0, v[34:35], off
	v_add_u32_e32 v11, v21, v29
	s_waitcnt vmcnt(0)
	v_pk_mul_f32 v[34:35], v[52:53], v[0:1] op_sel_hi:[1,0]
	v_pk_mul_f32 v[36:37], v[50:51], v[0:1] op_sel_hi:[1,0]
	ds_write2_b32 v11, v36, v37 offset1:1
	ds_write2_b32 v11, v34, v35 offset0:2 offset1:3
	v_or_b32_e32 v34, s34, v30
	v_ashrrev_i32_e32 v35, 31, v34
	v_lshl_add_u64 v[34:35], v[34:35], 2, s[26:27]
	global_load_dword v0, v[34:35], off
	s_waitcnt vmcnt(0)
	v_pk_mul_f32 v[34:35], v[56:57], v[0:1] op_sel_hi:[1,0]
	v_pk_mul_f32 v[36:37], v[54:55], v[0:1] op_sel_hi:[1,0]
	v_add_u32_e32 v0, 0x420, v11
	ds_write2_b32 v0, v36, v37 offset1:1
	v_add_u32_e32 v0, 0x428, v11
	ds_write2_b32 v0, v34, v35 offset1:1
	v_or_b32_e32 v34, s34, v31
	v_ashrrev_i32_e32 v35, 31, v34
	v_lshl_add_u64 v[34:35], v[34:35], 2, s[26:27]
	global_load_dword v0, v[34:35], off
	s_waitcnt vmcnt(0)
	v_pk_mul_f32 v[8:9], v[8:9], v[0:1] op_sel_hi:[1,0]
	v_pk_mul_f32 v[6:7], v[6:7], v[0:1] op_sel_hi:[1,0]
	v_add_u32_e32 v0, 0x840, v11
	ds_write2_b32 v0, v6, v7 offset1:1
	v_or_b32_e32 v6, s34, v32
	v_ashrrev_i32_e32 v7, 31, v6
	v_add_u32_e32 v0, 0x848, v11
	v_lshl_add_u64 v[6:7], v[6:7], 2, s[26:27]
	ds_write2_b32 v0, v8, v9 offset1:1
	global_load_dword v0, v[6:7], off
	v_lshl_add_u64 v[6:7], s[34:35], 1, v[14:15]
	s_waitcnt vmcnt(0)
	v_pk_mul_f32 v[4:5], v[4:5], v[0:1] op_sel_hi:[1,0]
	v_pk_mul_f32 v[2:3], v[2:3], v[0:1] op_sel_hi:[1,0]
	v_add_u32_e32 v0, 0xc60, v11
	ds_write2_b32 v0, v2, v3 offset1:1
	v_add_u32_e32 v0, 0xc68, v11
	ds_write2_b32 v0, v4, v5 offset1:1
	s_waitcnt lgkmcnt(0)
	ds_read2_b32 v[8:9], v24 offset0:33 offset1:41
	ds_read2_b32 v[34:35], v24 offset1:8
	ds_read2_b32 v[36:37], v24 offset0:66 offset1:74
	ds_read2_b32 v[38:39], v24 offset0:99 offset1:107
	ds_read2_b32 v[40:41], v24 offset0:132 offset1:140
	ds_read2_b32 v[42:43], v24 offset0:165 offset1:173
	ds_read2_b32 v[44:45], v24 offset0:198 offset1:206
	ds_read2_b32 v[46:47], v24 offset0:231 offset1:239
	v_add_u32_e32 v11, s36, v13
	v_add_u32_e32 v0, 0xc80, v11
	v_lshlrev_b64 v[48:49], 12, v[0:1]
	s_waitcnt lgkmcnt(6)
	v_cvt_pk_bf16_f32 v2, v34, v8
	s_waitcnt lgkmcnt(4)
	v_cvt_pk_bf16_f32 v3, v36, v38
	s_waitcnt lgkmcnt(2)
	v_cvt_pk_bf16_f32 v4, v40, v42
	s_waitcnt lgkmcnt(0)
	v_cvt_pk_bf16_f32 v5, v44, v46
	v_lshl_add_u64 v[48:49], v[6:7], 0, v[48:49]
	v_add_u32_e32 v0, 0xc88, v11
	global_store_dwordx4 v[48:49], v[2:5], off
	s_nop 1
	v_cvt_pk_bf16_f32 v2, v35, v9
	v_lshlrev_b64 v[8:9], 12, v[0:1]
	v_cvt_pk_bf16_f32 v3, v37, v39
	v_cvt_pk_bf16_f32 v4, v41, v43
	v_cvt_pk_bf16_f32 v5, v45, v47
	v_lshl_add_u64 v[8:9], v[6:7], 0, v[8:9]
	global_store_dwordx4 v[8:9], v[2:5], off
	ds_read2_b32 v[8:9], v24 offset0:49 offset1:57
	ds_read2_b32 v[34:35], v24 offset0:16 offset1:24
	ds_read2_b32 v[36:37], v24 offset0:82 offset1:90
	ds_read2_b32 v[38:39], v24 offset0:115 offset1:123
	ds_read2_b32 v[40:41], v24 offset0:148 offset1:156
	ds_read2_b32 v[42:43], v24 offset0:181 offset1:189
	ds_read2_b32 v[44:45], v24 offset0:214 offset1:222
	ds_read2_b32 v[46:47], v24 offset0:247 offset1:255
	v_add_u32_e32 v0, 0xc90, v11
	v_lshlrev_b64 v[48:49], 12, v[0:1]
	s_waitcnt lgkmcnt(6)
	v_cvt_pk_bf16_f32 v2, v34, v8
	s_waitcnt lgkmcnt(4)
	v_cvt_pk_bf16_f32 v3, v36, v38
	s_waitcnt lgkmcnt(2)
	v_cvt_pk_bf16_f32 v4, v40, v42
	s_waitcnt lgkmcnt(0)
	v_cvt_pk_bf16_f32 v5, v44, v46
	v_lshl_add_u64 v[48:49], v[6:7], 0, v[48:49]
	v_add_u32_e32 v0, 0xc98, v11
	global_store_dwordx4 v[48:49], v[2:5], off
	s_nop 1
	v_cvt_pk_bf16_f32 v2, v35, v9
	v_lshlrev_b64 v[8:9], 12, v[0:1]
	v_cvt_pk_bf16_f32 v3, v37, v39
	v_cvt_pk_bf16_f32 v4, v41, v43
	v_cvt_pk_bf16_f32 v5, v45, v47
	v_lshl_add_u64 v[6:7], v[6:7], 0, v[8:9]
	global_store_dwordx4 v[6:7], v[2:5], off
	s_waitcnt lgkmcnt(0)
	s_cbranch_execnz .LBB0_1079
	s_branch .LBB0_1078

.LBB0_1087:
	s_ashr_i32 s11, s9, 31
	s_lshr_b32 s11, s11, 30
	s_add_i32 s11, s9, s11
	s_ashr_i32 s11, s11, 2
	s_lshl_b32 s18, s11, 6
	s_lshl_b32 s11, s11, 7
	s_andn2_b64 vcc, exec, s[14:15]
	s_sub_i32 s11, 0, s11
	s_cbranch_vccnz .LBB0_1089
	s_add_i32 s26, s10, s11
	v_or_b32_e32 v8, s18, v20
	s_ashr_i32 s27, s26, 31
	v_ashrrev_i32_e32 v9, 31, v8
	v_or_b32_e32 v34, 8, v8
	v_or_b32_e32 v38, 16, v8
	v_lshl_add_u64 v[18:19], s[26:27], 2, v[2:3]
	v_lshlrev_b64 v[4:5], 9, v[8:9]
	v_ashrrev_i32_e32 v35, 31, v34
	v_ashrrev_i32_e32 v39, 31, v38
	v_lshl_add_u64 v[4:5], v[18:19], 0, v[4:5]
	v_lshlrev_b64 v[34:35], 9, v[34:35]
	v_lshlrev_b64 v[38:39], 9, v[38:39]
	v_or_b32_e32 v42, 24, v8
	global_load_dwordx4 v[4:7], v[4:5], off nt
	v_lshl_add_u64 v[34:35], v[18:19], 0, v[34:35]
	v_lshl_add_u64 v[38:39], v[18:19], 0, v[38:39]
	v_ashrrev_i32_e32 v43, 31, v42
	v_or_b32_e32 v46, 32, v8
	global_load_dwordx4 v[34:37], v[34:35], off nt
	v_lshlrev_b64 v[42:43], 9, v[42:43]
	global_load_dwordx4 v[38:41], v[38:39], off nt
	v_ashrrev_i32_e32 v47, 31, v46
	v_lshl_add_u64 v[42:43], v[18:19], 0, v[42:43]
	v_lshlrev_b64 v[46:47], 9, v[46:47]
	v_or_b32_e32 v50, 40, v8
	global_load_dwordx4 v[42:45], v[42:43], off nt
	v_lshl_add_u64 v[46:47], v[18:19], 0, v[46:47]
	v_ashrrev_i32_e32 v51, 31, v50
	global_load_dwordx4 v[46:49], v[46:47], off nt
	v_lshlrev_b64 v[50:51], 9, v[50:51]
	v_or_b32_e32 v54, 48, v8
	v_lshl_add_u64 v[50:51], v[18:19], 0, v[50:51]
	v_ashrrev_i32_e32 v55, 31, v54
	global_load_dwordx4 v[50:53], v[50:51], off nt
	v_lshlrev_b64 v[54:55], 9, v[54:55]
	v_or_b32_e32 v8, 56, v8
	v_lshl_add_u64 v[54:55], v[18:19], 0, v[54:55]
	v_ashrrev_i32_e32 v9, 31, v8
	global_load_dwordx4 v[54:57], v[54:55], off nt
	v_lshlrev_b64 v[8:9], 9, v[8:9]
	v_lshl_add_u64 v[8:9], v[18:19], 0, v[8:9]
	global_load_dwordx4 v[58:61], v[8:9], off nt
	v_add_u32_e32 v0, v21, v23
	v_add_u32_e32 v11, s26, v20
	s_ashr_i32 s19, s18, 31
	s_waitcnt vmcnt(7)
	ds_write2_b32 v22, v4, v5 offset1:1
	ds_write2_b32 v22, v6, v7 offset0:2 offset1:3
	v_add_u32_e32 v4, 0x420, v0
	s_waitcnt vmcnt(6)
	ds_write2_b32 v0, v34, v35 offset1:1
	ds_write2_b32 v0, v36, v37 offset0:2 offset1:3
	s_waitcnt vmcnt(5)
	ds_write2_b32 v4, v38, v39 offset1:1
	v_add_u32_e32 v4, 0x428, v0
	ds_write2_b32 v4, v40, v41 offset1:1
	v_add_u32_e32 v4, 0x840, v0
	v_add_u32_e32 v0, 0x848, v0
	s_waitcnt vmcnt(4)
	ds_write2_b32 v0, v44, v45 offset1:1
	v_add_u32_e32 v0, 0x1080, v22
	ds_write2_b32 v4, v42, v43 offset1:1
	s_waitcnt vmcnt(3)
	ds_write2_b32 v0, v46, v47 offset1:1
	v_add_u32_e32 v0, 0x1088, v22
	ds_write2_b32 v0, v48, v49 offset1:1
	v_add_u32_e32 v0, 0x14a0, v22
	v_lshl_add_u64 v[4:5], s[18:19], 1, v[16:17]
	s_waitcnt vmcnt(2)
	ds_write2_b32 v0, v50, v51 offset1:1
	v_add_u32_e32 v0, 0x14a8, v22
	ds_write2_b32 v0, v52, v53 offset1:1
	v_add_u32_e32 v0, 0x18c0, v22
	s_waitcnt vmcnt(1)
	ds_write2_b32 v0, v54, v55 offset1:1
	v_add_u32_e32 v0, 0x18c8, v22
	ds_write2_b32 v0, v56, v57 offset1:1
	v_add_u32_e32 v0, 0x1ce0, v22
	s_waitcnt vmcnt(0)
	ds_write2_b32 v0, v58, v59 offset1:1
	v_add_u32_e32 v0, 0x1ce8, v22
	ds_write2_b32 v0, v60, v61 offset1:1
	s_waitcnt lgkmcnt(0)
	ds_read2_b32 v[18:19], v24 offset0:33 offset1:41
	ds_read2_b32 v[34:35], v24 offset1:8
	ds_read2_b32 v[36:37], v24 offset0:66 offset1:74
	ds_read2_b32 v[38:39], v24 offset0:99 offset1:107
	ds_read2_b32 v[40:41], v24 offset0:132 offset1:140
	ds_read2_b32 v[42:43], v24 offset0:165 offset1:173
	ds_read2_b32 v[44:45], v24 offset0:198 offset1:206
	ds_read2_b32 v[46:47], v24 offset0:231 offset1:239
	v_add_u32_e32 v0, 0xd00, v11
	v_lshlrev_b64 v[48:49], 12, v[0:1]
	s_waitcnt lgkmcnt(6)
	v_cvt_pk_bf16_f32 v6, v34, v18
	s_waitcnt lgkmcnt(4)
	v_cvt_pk_bf16_f32 v7, v36, v38
	s_waitcnt lgkmcnt(2)
	v_cvt_pk_bf16_f32 v8, v40, v42
	s_waitcnt lgkmcnt(0)
	v_cvt_pk_bf16_f32 v9, v44, v46
	v_lshl_add_u64 v[48:49], v[4:5], 0, v[48:49]
	v_add_u32_e32 v0, 0xd08, v11
	global_store_dwordx4 v[48:49], v[6:9], off
	s_nop 1
	v_cvt_pk_bf16_f32 v6, v35, v19
	v_lshlrev_b64 v[18:19], 12, v[0:1]
	v_cvt_pk_bf16_f32 v7, v37, v39
	v_cvt_pk_bf16_f32 v8, v41, v43
	v_cvt_pk_bf16_f32 v9, v45, v47
	v_lshl_add_u64 v[18:19], v[4:5], 0, v[18:19]
	global_store_dwordx4 v[18:19], v[6:9], off
	ds_read2_b32 v[18:19], v24 offset0:49 offset1:57
	ds_read2_b32 v[34:35], v24 offset0:16 offset1:24
	ds_read2_b32 v[36:37], v24 offset0:82 offset1:90
	ds_read2_b32 v[38:39], v24 offset0:115 offset1:123
	ds_read2_b32 v[40:41], v24 offset0:148 offset1:156
	ds_read2_b32 v[42:43], v24 offset0:181 offset1:189
	ds_read2_b32 v[44:45], v24 offset0:214 offset1:222
	ds_read2_b32 v[46:47], v24 offset0:247 offset1:255
	v_add_u32_e32 v0, 0xd10, v11
	v_lshlrev_b64 v[48:49], 12, v[0:1]
	s_waitcnt lgkmcnt(6)
	v_cvt_pk_bf16_f32 v6, v34, v18
	s_waitcnt lgkmcnt(4)
	v_cvt_pk_bf16_f32 v7, v36, v38
	s_waitcnt lgkmcnt(2)
	v_cvt_pk_bf16_f32 v8, v40, v42
	s_waitcnt lgkmcnt(0)
	v_cvt_pk_bf16_f32 v9, v44, v46
	v_lshl_add_u64 v[48:49], v[4:5], 0, v[48:49]
	v_add_u32_e32 v0, 0xd18, v11
	global_store_dwordx4 v[48:49], v[6:9], off
	s_nop 1
	v_cvt_pk_bf16_f32 v6, v35, v19
	v_lshlrev_b64 v[18:19], 12, v[0:1]
	v_cvt_pk_bf16_f32 v7, v37, v39
	v_cvt_pk_bf16_f32 v8, v41, v43
	v_cvt_pk_bf16_f32 v9, v45, v47
	v_lshl_add_u64 v[4:5], v[4:5], 0, v[18:19]
	global_store_dwordx4 v[4:5], v[6:9], off
	s_waitcnt lgkmcnt(0)
	s_cbranch_execnz .LBB0_1086
	s_branch .LBB0_1085

.LBB0_1094:
	s_ashr_i32 s11, s9, 31
	s_lshr_b32 s11, s11, 30
	s_add_i32 s11, s9, s11
	s_ashr_i32 s11, s11, 2
	s_lshl_b32 s24, s11, 6
	s_lshl_b32 s11, s11, 7
	s_andn2_b64 vcc, exec, s[18:19]
	s_sub_i32 s11, 0, s11
	s_cbranch_vccnz .LBB0_1096
	s_add_i32 s26, s10, s11
	v_or_b32_e32 v18, s24, v20
	s_ashr_i32 s27, s26, 31
	v_ashrrev_i32_e32 v19, 31, v18
	v_lshl_add_u64 v[2:3], s[26:27], 2, v[16:17]
	v_lshlrev_b64 v[4:5], 9, v[18:19]
	v_lshl_add_u64 v[4:5], v[2:3], 0, v[4:5]
	global_load_dwordx4 v[34:37], v[4:5], off nt
	v_or_b32_e32 v4, 8, v18
	v_ashrrev_i32_e32 v5, 31, v4
	v_lshlrev_b64 v[4:5], 9, v[4:5]
	v_lshl_add_u64 v[4:5], v[2:3], 0, v[4:5]
	global_load_dwordx4 v[38:41], v[4:5], off nt
	v_or_b32_e32 v4, 16, v18
	v_ashrrev_i32_e32 v5, 31, v4
	v_lshlrev_b64 v[4:5], 9, v[4:5]
	v_lshl_add_u64 v[4:5], v[2:3], 0, v[4:5]
	global_load_dwordx4 v[42:45], v[4:5], off nt
	v_or_b32_e32 v4, 24, v18
	v_ashrrev_i32_e32 v5, 31, v4
	v_lshlrev_b64 v[4:5], 9, v[4:5]
	v_lshl_add_u64 v[4:5], v[2:3], 0, v[4:5]
	global_load_dwordx4 v[46:49], v[4:5], off nt
	v_or_b32_e32 v4, 32, v18
	v_ashrrev_i32_e32 v5, 31, v4
	v_lshlrev_b64 v[4:5], 9, v[4:5]
	v_lshl_add_u64 v[4:5], v[2:3], 0, v[4:5]
	global_load_dwordx4 v[50:53], v[4:5], off nt
	v_or_b32_e32 v4, 40, v18
	v_ashrrev_i32_e32 v5, 31, v4
	v_lshlrev_b64 v[4:5], 9, v[4:5]
	v_lshl_add_u64 v[4:5], v[2:3], 0, v[4:5]
	global_load_dwordx4 v[54:57], v[4:5], off nt
	v_or_b32_e32 v4, 48, v18
	v_ashrrev_i32_e32 v5, 31, v4
	v_lshlrev_b64 v[4:5], 9, v[4:5]
	v_lshl_add_u64 v[4:5], v[2:3], 0, v[4:5]
	global_load_dwordx4 v[6:9], v[4:5], off nt
	v_or_b32_e32 v4, 56, v18
	v_lshl_add_u64 v[18:19], v[18:19], 2, s[14:15]
	global_load_dword v0, v[18:19], off
	v_ashrrev_i32_e32 v5, 31, v4
	v_lshlrev_b64 v[4:5], 9, v[4:5]
	v_lshl_add_u64 v[2:3], v[2:3], 0, v[4:5]
	global_load_dwordx4 v[2:5], v[2:3], off nt
	v_add_u32_e32 v11, v21, v23
	s_ashr_i32 s25, s24, 31
	s_waitcnt vmcnt(1)
	v_pk_mul_f32 v[18:19], v[36:37], v[0:1] op_sel_hi:[1,0]
	v_pk_mul_f32 v[34:35], v[34:35], v[0:1] op_sel_hi:[1,0]
	ds_write2_b32 v22, v34, v35 offset1:1
	ds_write2_b32 v22, v18, v19 offset0:2 offset1:3
	v_or_b32_e32 v18, s24, v26
	v_ashrrev_i32_e32 v19, 31, v18
	v_lshl_add_u64 v[18:19], v[18:19], 2, s[14:15]
	global_load_dword v0, v[18:19], off
	s_waitcnt vmcnt(0)
	v_pk_mul_f32 v[18:19], v[40:41], v[0:1] op_sel_hi:[1,0]
	v_pk_mul_f32 v[34:35], v[38:39], v[0:1] op_sel_hi:[1,0]
	ds_write2_b32 v11, v34, v35 offset1:1
	ds_write2_b32 v11, v18, v19 offset0:2 offset1:3
	v_or_b32_e32 v18, s24, v27
	v_ashrrev_i32_e32 v19, 31, v18
	v_lshl_add_u64 v[18:19], v[18:19], 2, s[14:15]
	global_load_dword v0, v[18:19], off
	s_waitcnt vmcnt(0)
	v_pk_mul_f32 v[18:19], v[44:45], v[0:1] op_sel_hi:[1,0]
	v_pk_mul_f32 v[34:35], v[42:43], v[0:1] op_sel_hi:[1,0]
	v_add_u32_e32 v0, 0x420, v11
	ds_write2_b32 v0, v34, v35 offset1:1
	v_add_u32_e32 v0, 0x428, v11
	ds_write2_b32 v0, v18, v19 offset1:1
	v_or_b32_e32 v18, s24, v25
	v_ashrrev_i32_e32 v19, 31, v18
	v_lshl_add_u64 v[18:19], v[18:19], 2, s[14:15]
	global_load_dword v0, v[18:19], off
	s_waitcnt vmcnt(0)
	v_pk_mul_f32 v[18:19], v[48:49], v[0:1] op_sel_hi:[1,0]
	v_pk_mul_f32 v[34:35], v[46:47], v[0:1] op_sel_hi:[1,0]
	v_add_u32_e32 v0, 0x840, v11
	ds_write2_b32 v0, v34, v35 offset1:1
	v_add_u32_e32 v0, 0x848, v11
	ds_write2_b32 v0, v18, v19 offset1:1
	v_or_b32_e32 v18, s24, v28
	v_ashrrev_i32_e32 v19, 31, v18
	v_lshl_add_u64 v[18:19], v[18:19], 2, s[14:15]
	global_load_dword v0, v[18:19], off
	v_add_u32_e32 v11, v21, v29
	s_waitcnt vmcnt(0)
	v_pk_mul_f32 v[18:19], v[52:53], v[0:1] op_sel_hi:[1,0]
	v_pk_mul_f32 v[34:35], v[50:51], v[0:1] op_sel_hi:[1,0]
	ds_write2_b32 v11, v34, v35 offset1:1
	ds_write2_b32 v11, v18, v19 offset0:2 offset1:3
	v_or_b32_e32 v18, s24, v30
	v_ashrrev_i32_e32 v19, 31, v18
	v_lshl_add_u64 v[18:19], v[18:19], 2, s[14:15]
	global_load_dword v0, v[18:19], off
	s_waitcnt vmcnt(0)
	v_pk_mul_f32 v[18:19], v[56:57], v[0:1] op_sel_hi:[1,0]
	v_pk_mul_f32 v[34:35], v[54:55], v[0:1] op_sel_hi:[1,0]
	v_add_u32_e32 v0, 0x420, v11
	ds_write2_b32 v0, v34, v35 offset1:1
	v_add_u32_e32 v0, 0x428, v11
	ds_write2_b32 v0, v18, v19 offset1:1
	v_or_b32_e32 v18, s24, v31
	v_ashrrev_i32_e32 v19, 31, v18
	v_lshl_add_u64 v[18:19], v[18:19], 2, s[14:15]
	global_load_dword v0, v[18:19], off
	s_waitcnt vmcnt(0)
	v_pk_mul_f32 v[8:9], v[8:9], v[0:1] op_sel_hi:[1,0]
	v_pk_mul_f32 v[6:7], v[6:7], v[0:1] op_sel_hi:[1,0]
	v_add_u32_e32 v0, 0x840, v11
	ds_write2_b32 v0, v6, v7 offset1:1
	v_or_b32_e32 v6, s24, v32
	v_ashrrev_i32_e32 v7, 31, v6
	v_add_u32_e32 v0, 0x848, v11
	v_lshl_add_u64 v[6:7], v[6:7], 2, s[14:15]
	ds_write2_b32 v0, v8, v9 offset1:1
	global_load_dword v0, v[6:7], off
	v_lshl_add_u64 v[6:7], s[24:25], 1, v[14:15]
	s_waitcnt vmcnt(0)
	v_pk_mul_f32 v[4:5], v[4:5], v[0:1] op_sel_hi:[1,0]
	v_pk_mul_f32 v[2:3], v[2:3], v[0:1] op_sel_hi:[1,0]
	v_add_u32_e32 v0, 0xc60, v11
	ds_write2_b32 v0, v2, v3 offset1:1
	v_add_u32_e32 v0, 0xc68, v11
	ds_write2_b32 v0, v4, v5 offset1:1
	s_waitcnt lgkmcnt(0)
	ds_read2_b32 v[8:9], v24 offset0:33 offset1:41
	ds_read2_b32 v[18:19], v24 offset1:8
	ds_read2_b32 v[34:35], v24 offset0:66 offset1:74
	ds_read2_b32 v[36:37], v24 offset0:99 offset1:107
	ds_read2_b32 v[38:39], v24 offset0:132 offset1:140
	ds_read2_b32 v[40:41], v24 offset0:165 offset1:173
	ds_read2_b32 v[42:43], v24 offset0:198 offset1:206
	ds_read2_b32 v[44:45], v24 offset0:231 offset1:239
	v_add_u32_e32 v11, s26, v20
	v_add_u32_e32 v0, 0xd00, v11
	v_lshlrev_b64 v[46:47], 12, v[0:1]
	s_waitcnt lgkmcnt(6)
	v_cvt_pk_bf16_f32 v2, v18, v8
	s_waitcnt lgkmcnt(4)
	v_cvt_pk_bf16_f32 v3, v34, v36
	s_waitcnt lgkmcnt(2)
	v_cvt_pk_bf16_f32 v4, v38, v40
	s_waitcnt lgkmcnt(0)
	v_cvt_pk_bf16_f32 v5, v42, v44
	v_lshl_add_u64 v[46:47], v[6:7], 0, v[46:47]
	v_add_u32_e32 v0, 0xd08, v11
	global_store_dwordx4 v[46:47], v[2:5], off
	s_nop 1
	v_cvt_pk_bf16_f32 v2, v19, v9
	v_lshlrev_b64 v[8:9], 12, v[0:1]
	v_cvt_pk_bf16_f32 v3, v35, v37
	v_cvt_pk_bf16_f32 v4, v39, v41
	v_cvt_pk_bf16_f32 v5, v43, v45
	v_lshl_add_u64 v[8:9], v[6:7], 0, v[8:9]
	global_store_dwordx4 v[8:9], v[2:5], off
	ds_read2_b32 v[8:9], v24 offset0:49 offset1:57
	ds_read2_b32 v[18:19], v24 offset0:16 offset1:24
	ds_read2_b32 v[34:35], v24 offset0:82 offset1:90
	ds_read2_b32 v[36:37], v24 offset0:115 offset1:123
	ds_read2_b32 v[38:39], v24 offset0:148 offset1:156
	ds_read2_b32 v[40:41], v24 offset0:181 offset1:189
	ds_read2_b32 v[42:43], v24 offset0:214 offset1:222
	ds_read2_b32 v[44:45], v24 offset0:247 offset1:255
	v_add_u32_e32 v0, 0xd10, v11
	v_lshlrev_b64 v[46:47], 12, v[0:1]
	s_waitcnt lgkmcnt(6)
	v_cvt_pk_bf16_f32 v2, v18, v8
	s_waitcnt lgkmcnt(4)
	v_cvt_pk_bf16_f32 v3, v34, v36
	s_waitcnt lgkmcnt(2)
	v_cvt_pk_bf16_f32 v4, v38, v40
	s_waitcnt lgkmcnt(0)
	v_cvt_pk_bf16_f32 v5, v42, v44
	v_lshl_add_u64 v[46:47], v[6:7], 0, v[46:47]
	v_add_u32_e32 v0, 0xd18, v11
	global_store_dwordx4 v[46:47], v[2:5], off
	s_nop 1
	v_cvt_pk_bf16_f32 v2, v19, v9
	v_lshlrev_b64 v[8:9], 12, v[0:1]
	v_cvt_pk_bf16_f32 v3, v35, v37
	v_cvt_pk_bf16_f32 v4, v39, v41
	v_cvt_pk_bf16_f32 v5, v43, v45
	v_lshl_add_u64 v[6:7], v[6:7], 0, v[8:9]
	global_store_dwordx4 v[6:7], v[2:5], off
	s_waitcnt lgkmcnt(0)
	s_cbranch_execnz .LBB0_1093
	s_branch .LBB0_1092

.LBB0_1116:
	s_ashr_i32 s14, s22, 31
	s_lshr_b32 s14, s14, 27
	s_add_i32 s14, s22, s14
	s_ashr_i32 s15, s14, 5
	s_lshl_b32 s14, s15, 6
	s_lshl_b32 s15, s15, 10
	s_andn2_b64 vcc, exec, s[6:7]
	s_sub_i32 s24, 0, s15
	s_cbranch_vccnz .LBB0_1118
	v_or_b32_e32 v50, s14, v20
	s_add_i32 s18, s23, s24
	v_or_b32_e32 v26, 8, v50
	v_or_b32_e32 v30, 16, v50
	s_ashr_i32 s19, s18, 31
	v_ashrrev_i32_e32 v51, 31, v50
	v_ashrrev_i32_e32 v27, 31, v26
	v_ashrrev_i32_e32 v31, 31, v30
	v_lshl_add_u64 v[52:53], s[18:19], 2, v[14:15]
	v_lshlrev_b64 v[16:17], 12, v[50:51]
	v_lshlrev_b64 v[26:27], 12, v[26:27]
	v_lshlrev_b64 v[30:31], 12, v[30:31]
	v_or_b32_e32 v34, 24, v50
	v_lshl_add_u64 v[16:17], v[52:53], 0, v[16:17]
	v_lshl_add_u64 v[26:27], v[52:53], 0, v[26:27]
	v_lshl_add_u64 v[30:31], v[52:53], 0, v[30:31]
	v_ashrrev_i32_e32 v35, 31, v34
	v_or_b32_e32 v38, 32, v50
	global_load_dwordx4 v[16:19], v[16:17], off nt
	v_lshlrev_b64 v[34:35], 12, v[34:35]
	global_load_dwordx4 v[26:29], v[26:27], off nt
	v_ashrrev_i32_e32 v39, 31, v38
	global_load_dwordx4 v[30:33], v[30:31], off nt
	v_lshl_add_u64 v[34:35], v[52:53], 0, v[34:35]
	v_lshlrev_b64 v[38:39], 12, v[38:39]
	v_or_b32_e32 v42, 40, v50
	global_load_dwordx4 v[34:37], v[34:35], off nt
	v_lshl_add_u64 v[38:39], v[52:53], 0, v[38:39]
	v_ashrrev_i32_e32 v43, 31, v42
	global_load_dwordx4 v[38:41], v[38:39], off nt
	v_lshlrev_b64 v[42:43], 12, v[42:43]
	v_or_b32_e32 v46, 48, v50
	v_lshl_add_u64 v[42:43], v[52:53], 0, v[42:43]
	v_ashrrev_i32_e32 v47, 31, v46
	global_load_dwordx4 v[42:45], v[42:43], off nt
	v_lshlrev_b64 v[46:47], 12, v[46:47]
	v_or_b32_e32 v50, 56, v50
	v_lshl_add_u64 v[46:47], v[52:53], 0, v[46:47]
	v_ashrrev_i32_e32 v51, 31, v50
	global_load_dwordx4 v[46:49], v[46:47], off nt
	v_lshlrev_b64 v[50:51], 12, v[50:51]
	v_lshl_add_u64 v[50:51], v[52:53], 0, v[50:51]
	global_load_dwordx4 v[50:53], v[50:51], off nt
	v_add_u32_e32 v11, v21, v23
	v_add_u32_e32 v13, 0x420, v11
	s_ashr_i32 s15, s14, 31
	s_waitcnt vmcnt(7)
	ds_write2_b32 v22, v16, v17 offset1:1
	ds_write2_b32 v22, v18, v19 offset0:2 offset1:3
	s_waitcnt vmcnt(6)
	ds_write2_b32 v11, v26, v27 offset1:1
	ds_write2_b32 v11, v28, v29 offset0:2 offset1:3
	v_lshl_add_u64 v[16:17], s[14:15], 1, v[8:9]
	s_waitcnt vmcnt(5)
	ds_write2_b32 v13, v30, v31 offset1:1
	v_add_u32_e32 v13, 0x428, v11
	ds_write2_b32 v13, v32, v33 offset1:1
	v_add_u32_e32 v13, 0x840, v11
	v_add_u32_e32 v11, 0x848, v11
	s_waitcnt vmcnt(4)
	ds_write2_b32 v11, v36, v37 offset1:1
	v_add_u32_e32 v11, 0x1080, v22
	s_waitcnt vmcnt(3)
	ds_write2_b32 v11, v38, v39 offset1:1
	v_add_u32_e32 v11, 0x1088, v22
	ds_write2_b32 v11, v40, v41 offset1:1
	v_add_u32_e32 v11, 0x14a0, v22
	ds_write2_b32 v13, v34, v35 offset1:1
	s_waitcnt vmcnt(2)
	ds_write2_b32 v11, v42, v43 offset1:1
	v_add_u32_e32 v11, 0x14a8, v22
	ds_write2_b32 v11, v44, v45 offset1:1
	v_add_u32_e32 v11, 0x18c0, v22
	v_add_u32_e32 v44, s18, v0
	s_waitcnt vmcnt(1)
	ds_write2_b32 v11, v46, v47 offset1:1
	v_add_u32_e32 v11, 0x18c8, v22
	ds_write2_b32 v11, v48, v49 offset1:1
	v_add_u32_e32 v11, 0x1ce0, v22
	s_waitcnt vmcnt(0)
	ds_write2_b32 v11, v50, v51 offset1:1
	v_add_u32_e32 v11, 0x1ce8, v22
	ds_write2_b32 v11, v52, v53 offset1:1
	s_waitcnt lgkmcnt(0)
	ds_read2_b32 v[18:19], v24 offset0:33 offset1:41
	ds_read2_b32 v[30:31], v24 offset1:8
	ds_read2_b32 v[32:33], v24 offset0:66 offset1:74
	ds_read2_b32 v[34:35], v24 offset0:99 offset1:107
	ds_read2_b32 v[36:37], v24 offset0:132 offset1:140
	ds_read2_b32 v[38:39], v24 offset0:165 offset1:173
	ds_read2_b32 v[40:41], v24 offset0:198 offset1:206
	ds_read2_b32 v[42:43], v24 offset0:231 offset1:239
	v_ashrrev_i32_e32 v45, 31, v44
	v_lshlrev_b64 v[46:47], 9, v[44:45]
	s_waitcnt lgkmcnt(6)
	v_cvt_pk_bf16_f32 v26, v30, v18
	s_waitcnt lgkmcnt(4)
	v_cvt_pk_bf16_f32 v27, v32, v34
	s_waitcnt lgkmcnt(2)
	v_cvt_pk_bf16_f32 v28, v36, v38
	s_waitcnt lgkmcnt(0)
	v_cvt_pk_bf16_f32 v29, v40, v42
	v_lshl_add_u64 v[46:47], v[16:17], 0, v[46:47]
	v_add_u32_e32 v18, 8, v44
	global_store_dwordx4 v[46:47], v[26:29], off
	v_add_u32_e32 v46, 16, v44
	v_ashrrev_i32_e32 v47, 31, v46
	v_cvt_pk_bf16_f32 v26, v31, v19
	v_ashrrev_i32_e32 v19, 31, v18
	v_lshlrev_b64 v[18:19], 9, v[18:19]
	v_cvt_pk_bf16_f32 v27, v33, v35
	v_cvt_pk_bf16_f32 v28, v37, v39
	v_cvt_pk_bf16_f32 v29, v41, v43
	v_lshl_add_u64 v[18:19], v[16:17], 0, v[18:19]
	global_store_dwordx4 v[18:19], v[26:29], off
	ds_read2_b32 v[18:19], v24 offset0:49 offset1:57
	ds_read2_b32 v[30:31], v24 offset0:16 offset1:24
	ds_read2_b32 v[32:33], v24 offset0:82 offset1:90
	ds_read2_b32 v[34:35], v24 offset0:115 offset1:123
	ds_read2_b32 v[36:37], v24 offset0:148 offset1:156
	ds_read2_b32 v[38:39], v24 offset0:181 offset1:189
	ds_read2_b32 v[40:41], v24 offset0:214 offset1:222
	ds_read2_b32 v[42:43], v24 offset0:247 offset1:255
	v_lshlrev_b64 v[46:47], 9, v[46:47]
	s_waitcnt lgkmcnt(6)
	v_cvt_pk_bf16_f32 v26, v30, v18
	s_waitcnt lgkmcnt(4)
	v_cvt_pk_bf16_f32 v27, v32, v34
	s_waitcnt lgkmcnt(2)
	v_cvt_pk_bf16_f32 v28, v36, v38
	s_waitcnt lgkmcnt(0)
	v_cvt_pk_bf16_f32 v29, v40, v42
	v_lshl_add_u64 v[46:47], v[16:17], 0, v[46:47]
	v_add_u32_e32 v18, 24, v44
	global_store_dwordx4 v[46:47], v[26:29], off
	s_nop 1
	v_cvt_pk_bf16_f32 v26, v31, v19
	v_ashrrev_i32_e32 v19, 31, v18
	v_lshlrev_b64 v[18:19], 9, v[18:19]
	v_cvt_pk_bf16_f32 v27, v33, v35
	v_cvt_pk_bf16_f32 v28, v37, v39
	v_cvt_pk_bf16_f32 v29, v41, v43
	v_lshl_add_u64 v[16:17], v[16:17], 0, v[18:19]
	global_store_dwordx4 v[16:17], v[26:29], off
	s_waitcnt lgkmcnt(0)
	s_cbranch_execnz .LBB0_1115
	s_branch .LBB0_1114

.LBB0_1123:
	s_ashr_i32 s12, s10, 31
	s_lshr_b32 s12, s12, 27
	s_add_i32 s12, s10, s12
	s_ashr_i32 s12, s12, 5
	s_lshl_b32 s14, s12, 6
	s_lshl_b32 s12, s12, 10
	s_andn2_b64 vcc, exec, s[6:7]
	s_sub_i32 s12, 0, s12
	s_cbranch_vccnz .LBB0_1125
	v_or_b32_e32 v8, s14, v20
	s_add_i32 s18, s11, s12
	v_or_b32_e32 v26, 8, v8
	v_or_b32_e32 v30, 16, v8
	s_ashr_i32 s19, s18, 31
	v_ashrrev_i32_e32 v9, 31, v8
	v_ashrrev_i32_e32 v27, 31, v26
	v_ashrrev_i32_e32 v31, 31, v30
	v_lshl_add_u64 v[18:19], s[18:19], 2, v[4:5]
	v_lshlrev_b64 v[14:15], 12, v[8:9]
	v_lshlrev_b64 v[26:27], 12, v[26:27]
	v_lshlrev_b64 v[30:31], 12, v[30:31]
	v_or_b32_e32 v34, 24, v8
	v_lshl_add_u64 v[14:15], v[18:19], 0, v[14:15]
	v_lshl_add_u64 v[26:27], v[18:19], 0, v[26:27]
	v_lshl_add_u64 v[30:31], v[18:19], 0, v[30:31]
	v_ashrrev_i32_e32 v35, 31, v34
	v_or_b32_e32 v38, 32, v8
	global_load_dwordx4 v[14:17], v[14:15], off nt
	v_lshlrev_b64 v[34:35], 12, v[34:35]
	global_load_dwordx4 v[26:29], v[26:27], off nt
	v_ashrrev_i32_e32 v39, 31, v38
	global_load_dwordx4 v[30:33], v[30:31], off nt
	v_lshl_add_u64 v[34:35], v[18:19], 0, v[34:35]
	v_lshlrev_b64 v[38:39], 12, v[38:39]
	v_or_b32_e32 v42, 40, v8
	global_load_dwordx4 v[34:37], v[34:35], off nt
	v_lshl_add_u64 v[38:39], v[18:19], 0, v[38:39]
	v_ashrrev_i32_e32 v43, 31, v42
	global_load_dwordx4 v[38:41], v[38:39], off nt
	v_lshlrev_b64 v[42:43], 12, v[42:43]
	v_or_b32_e32 v46, 48, v8
	v_lshl_add_u64 v[42:43], v[18:19], 0, v[42:43]
	v_ashrrev_i32_e32 v47, 31, v46
	global_load_dwordx4 v[42:45], v[42:43], off nt
	v_lshlrev_b64 v[46:47], 12, v[46:47]
	v_or_b32_e32 v8, 56, v8
	v_lshl_add_u64 v[46:47], v[18:19], 0, v[46:47]
	v_ashrrev_i32_e32 v9, 31, v8
	global_load_dwordx4 v[46:49], v[46:47], off nt
	v_lshlrev_b64 v[8:9], 12, v[8:9]
	v_lshl_add_u64 v[8:9], v[18:19], 0, v[8:9]
	global_load_dwordx4 v[50:53], v[8:9], off nt
	v_add_u32_e32 v0, v21, v23
	v_add_u32_e32 v8, 0x420, v0
	s_ashr_i32 s15, s14, 31
	s_waitcnt vmcnt(7)
	ds_write2_b32 v22, v14, v15 offset1:1
	ds_write2_b32 v22, v16, v17 offset0:2 offset1:3
	s_waitcnt vmcnt(6)
	ds_write2_b32 v0, v26, v27 offset1:1
	ds_write2_b32 v0, v28, v29 offset0:2 offset1:3
	s_waitcnt vmcnt(5)
	ds_write2_b32 v8, v30, v31 offset1:1
	v_add_u32_e32 v8, 0x428, v0
	ds_write2_b32 v8, v32, v33 offset1:1
	v_add_u32_e32 v8, 0x840, v0
	v_add_u32_e32 v0, 0x848, v0
	s_waitcnt vmcnt(4)
	ds_write2_b32 v0, v36, v37 offset1:1
	v_add_u32_e32 v0, 0x1080, v22
	s_waitcnt vmcnt(3)
	ds_write2_b32 v0, v38, v39 offset1:1
	v_add_u32_e32 v0, 0x1088, v22
	ds_write2_b32 v0, v40, v41 offset1:1
	v_add_u32_e32 v0, 0x14a0, v22
	ds_write2_b32 v8, v34, v35 offset1:1
	s_waitcnt vmcnt(2)
	ds_write2_b32 v0, v42, v43 offset1:1
	v_add_u32_e32 v0, 0x14a8, v22
	ds_write2_b32 v0, v44, v45 offset1:1
	v_add_u32_e32 v0, 0x18c0, v22
	v_add_u32_e32 v40, s18, v20
	s_waitcnt vmcnt(1)
	ds_write2_b32 v0, v46, v47 offset1:1
	v_add_u32_e32 v0, 0x18c8, v22
	ds_write2_b32 v0, v48, v49 offset1:1
	v_add_u32_e32 v0, 0x1ce0, v22
	s_waitcnt vmcnt(0)
	ds_write2_b32 v0, v50, v51 offset1:1
	v_add_u32_e32 v0, 0x1ce8, v22
	ds_write2_b32 v0, v52, v53 offset1:1
	s_waitcnt lgkmcnt(0)
	ds_read2_b32 v[18:19], v24 offset0:33 offset1:41
	ds_read2_b32 v[26:27], v24 offset1:8
	ds_read2_b32 v[28:29], v24 offset0:66 offset1:74
	ds_read2_b32 v[30:31], v24 offset0:99 offset1:107
	ds_read2_b32 v[32:33], v24 offset0:132 offset1:140
	ds_read2_b32 v[34:35], v24 offset0:165 offset1:173
	ds_read2_b32 v[36:37], v24 offset0:198 offset1:206
	ds_read2_b32 v[38:39], v24 offset0:231 offset1:239
	v_ashrrev_i32_e32 v41, 31, v40
	v_lshl_add_u64 v[8:9], s[14:15], 1, v[6:7]
	v_lshlrev_b64 v[42:43], 9, v[40:41]
	s_waitcnt lgkmcnt(6)
	v_cvt_pk_bf16_f32 v14, v26, v18
	s_waitcnt lgkmcnt(4)
	v_cvt_pk_bf16_f32 v15, v28, v30
	s_waitcnt lgkmcnt(2)
	v_cvt_pk_bf16_f32 v16, v32, v34
	s_waitcnt lgkmcnt(0)
	v_cvt_pk_bf16_f32 v17, v36, v38
	v_lshl_add_u64 v[42:43], v[8:9], 0, v[42:43]
	v_add_u32_e32 v18, 8, v40
	global_store_dwordx4 v[42:43], v[14:17], off
	v_add_u32_e32 v42, 16, v40
	v_ashrrev_i32_e32 v43, 31, v42
	v_cvt_pk_bf16_f32 v14, v27, v19
	v_ashrrev_i32_e32 v19, 31, v18
	v_lshlrev_b64 v[18:19], 9, v[18:19]
	v_cvt_pk_bf16_f32 v15, v29, v31
	v_cvt_pk_bf16_f32 v16, v33, v35
	v_cvt_pk_bf16_f32 v17, v37, v39
	v_lshl_add_u64 v[18:19], v[8:9], 0, v[18:19]
	global_store_dwordx4 v[18:19], v[14:17], off
	ds_read2_b32 v[18:19], v24 offset0:49 offset1:57
	ds_read2_b32 v[26:27], v24 offset0:16 offset1:24
	ds_read2_b32 v[28:29], v24 offset0:82 offset1:90
	ds_read2_b32 v[30:31], v24 offset0:115 offset1:123
	ds_read2_b32 v[32:33], v24 offset0:148 offset1:156
	ds_read2_b32 v[34:35], v24 offset0:181 offset1:189
	ds_read2_b32 v[36:37], v24 offset0:214 offset1:222
	ds_read2_b32 v[38:39], v24 offset0:247 offset1:255
	v_lshlrev_b64 v[42:43], 9, v[42:43]
	s_waitcnt lgkmcnt(6)
	v_cvt_pk_bf16_f32 v14, v26, v18
	s_waitcnt lgkmcnt(4)
	v_cvt_pk_bf16_f32 v15, v28, v30
	s_waitcnt lgkmcnt(2)
	v_cvt_pk_bf16_f32 v16, v32, v34
	s_waitcnt lgkmcnt(0)
	v_cvt_pk_bf16_f32 v17, v36, v38
	v_lshl_add_u64 v[42:43], v[8:9], 0, v[42:43]
	v_add_u32_e32 v18, 24, v40
	global_store_dwordx4 v[42:43], v[14:17], off
	s_nop 1
	v_cvt_pk_bf16_f32 v14, v27, v19
	v_ashrrev_i32_e32 v19, 31, v18
	v_lshlrev_b64 v[18:19], 9, v[18:19]
	v_cvt_pk_bf16_f32 v15, v29, v31
	v_cvt_pk_bf16_f32 v16, v33, v35
	v_cvt_pk_bf16_f32 v17, v37, v39
	v_lshl_add_u64 v[8:9], v[8:9], 0, v[18:19]
	global_store_dwordx4 v[8:9], v[14:17], off
	s_waitcnt lgkmcnt(0)
	s_cbranch_execnz .LBB0_1122
	s_branch .LBB0_1121

.LBB0_1132:
	s_ashr_i32 s10, s8, 31
	s_lshr_b32 s10, s10, 27
	s_add_i32 s10, s8, s10
	s_ashr_i32 s10, s10, 5
	s_lshl_b32 s14, s10, 6
	s_lshl_b32 s10, s10, 10
	s_andn2_b64 vcc, exec, s[6:7]
	s_sub_i32 s10, 0, s10
	s_cbranch_vccnz .LBB0_1134
	s_add_i32 s18, s9, s10
	v_or_b32_e32 v18, s14, v20
	s_ashr_i32 s19, s18, 31
	v_ashrrev_i32_e32 v19, 31, v18
	v_or_b32_e32 v14, 8, v18
	v_or_b32_e32 v26, 16, v18
	v_lshl_add_u64 v[46:47], s[18:19], 2, v[2:3]
	v_lshlrev_b64 v[6:7], 12, v[18:19]
	v_ashrrev_i32_e32 v15, 31, v14
	v_ashrrev_i32_e32 v27, 31, v26
	v_lshl_add_u64 v[6:7], v[46:47], 0, v[6:7]
	v_lshlrev_b64 v[14:15], 12, v[14:15]
	v_lshlrev_b64 v[26:27], 12, v[26:27]
	v_or_b32_e32 v30, 24, v18
	global_load_dwordx4 v[6:9], v[6:7], off nt
	v_lshl_add_u64 v[14:15], v[46:47], 0, v[14:15]
	v_lshl_add_u64 v[26:27], v[46:47], 0, v[26:27]
	v_ashrrev_i32_e32 v31, 31, v30
	v_or_b32_e32 v34, 32, v18
	global_load_dwordx4 v[14:17], v[14:15], off nt
	v_lshlrev_b64 v[30:31], 12, v[30:31]
	global_load_dwordx4 v[26:29], v[26:27], off nt
	v_ashrrev_i32_e32 v35, 31, v34
	v_lshl_add_u64 v[30:31], v[46:47], 0, v[30:31]
	v_lshlrev_b64 v[34:35], 12, v[34:35]
	v_or_b32_e32 v38, 40, v18
	global_load_dwordx4 v[30:33], v[30:31], off nt
	v_lshl_add_u64 v[34:35], v[46:47], 0, v[34:35]
	v_ashrrev_i32_e32 v39, 31, v38
	global_load_dwordx4 v[34:37], v[34:35], off nt
	v_lshlrev_b64 v[38:39], 12, v[38:39]
	v_or_b32_e32 v42, 48, v18
	v_lshl_add_u64 v[38:39], v[46:47], 0, v[38:39]
	v_ashrrev_i32_e32 v43, 31, v42
	global_load_dwordx4 v[38:41], v[38:39], off nt
	v_lshlrev_b64 v[42:43], 12, v[42:43]
	v_or_b32_e32 v18, 56, v18
	v_lshl_add_u64 v[42:43], v[46:47], 0, v[42:43]
	v_ashrrev_i32_e32 v19, 31, v18
	global_load_dwordx4 v[42:45], v[42:43], off nt
	v_lshlrev_b64 v[18:19], 12, v[18:19]
	v_lshl_add_u64 v[18:19], v[46:47], 0, v[18:19]
	global_load_dwordx4 v[46:49], v[18:19], off nt
	v_add_u32_e32 v0, v21, v23
	s_ashr_i32 s15, s14, 31
	s_waitcnt vmcnt(7)
	ds_write2_b32 v22, v6, v7 offset1:1
	ds_write2_b32 v22, v8, v9 offset0:2 offset1:3
	v_add_u32_e32 v6, 0x420, v0
	s_waitcnt vmcnt(6)
	ds_write2_b32 v0, v14, v15 offset1:1
	ds_write2_b32 v0, v16, v17 offset0:2 offset1:3
	s_waitcnt vmcnt(5)
	ds_write2_b32 v6, v26, v27 offset1:1
	v_add_u32_e32 v6, 0x428, v0
	ds_write2_b32 v6, v28, v29 offset1:1
	v_add_u32_e32 v6, 0x840, v0
	v_add_u32_e32 v0, 0x848, v0
	s_waitcnt vmcnt(4)
	ds_write2_b32 v0, v32, v33 offset1:1
	v_add_u32_e32 v0, 0x1080, v22
	ds_write2_b32 v6, v30, v31 offset1:1
	s_waitcnt vmcnt(3)
	ds_write2_b32 v0, v34, v35 offset1:1
	v_add_u32_e32 v0, 0x1088, v22
	ds_write2_b32 v0, v36, v37 offset1:1
	v_add_u32_e32 v0, 0x14a0, v22
	v_lshl_add_u64 v[6:7], s[14:15], 1, v[4:5]
	s_waitcnt vmcnt(2)
	ds_write2_b32 v0, v38, v39 offset1:1
	v_add_u32_e32 v0, 0x14a8, v22
	ds_write2_b32 v0, v40, v41 offset1:1
	v_add_u32_e32 v0, 0x18c0, v22
	v_add_u32_e32 v38, s18, v20
	s_waitcnt vmcnt(1)
	ds_write2_b32 v0, v42, v43 offset1:1
	v_add_u32_e32 v0, 0x18c8, v22
	ds_write2_b32 v0, v44, v45 offset1:1
	v_add_u32_e32 v0, 0x1ce0, v22
	s_waitcnt vmcnt(0)
	ds_write2_b32 v0, v46, v47 offset1:1
	v_add_u32_e32 v0, 0x1ce8, v22
	ds_write2_b32 v0, v48, v49 offset1:1
	s_waitcnt lgkmcnt(0)
	ds_read2_b32 v[8:9], v24 offset0:33 offset1:41
	ds_read2_b32 v[18:19], v24 offset1:8
	ds_read2_b32 v[26:27], v24 offset0:66 offset1:74
	ds_read2_b32 v[28:29], v24 offset0:99 offset1:107
	ds_read2_b32 v[30:31], v24 offset0:132 offset1:140
	ds_read2_b32 v[32:33], v24 offset0:165 offset1:173
	ds_read2_b32 v[34:35], v24 offset0:198 offset1:206
	ds_read2_b32 v[36:37], v24 offset0:231 offset1:239
	v_ashrrev_i32_e32 v39, 31, v38
	v_lshlrev_b64 v[40:41], 11, v[38:39]
	s_waitcnt lgkmcnt(6)
	v_cvt_pk_bf16_f32 v14, v18, v8
	s_waitcnt lgkmcnt(4)
	v_cvt_pk_bf16_f32 v15, v26, v28
	s_waitcnt lgkmcnt(2)
	v_cvt_pk_bf16_f32 v16, v30, v32
	s_waitcnt lgkmcnt(0)
	v_cvt_pk_bf16_f32 v17, v34, v36
	v_lshl_add_u64 v[40:41], v[6:7], 0, v[40:41]
	v_add_u32_e32 v8, 8, v38
	global_store_dwordx4 v[40:41], v[14:17], off
	v_add_u32_e32 v40, 16, v38
	v_ashrrev_i32_e32 v41, 31, v40
	v_cvt_pk_bf16_f32 v14, v19, v9
	v_ashrrev_i32_e32 v9, 31, v8
	v_lshlrev_b64 v[8:9], 11, v[8:9]
	v_cvt_pk_bf16_f32 v15, v27, v29
	v_cvt_pk_bf16_f32 v16, v31, v33
	v_cvt_pk_bf16_f32 v17, v35, v37
	v_lshl_add_u64 v[8:9], v[6:7], 0, v[8:9]
	global_store_dwordx4 v[8:9], v[14:17], off
	ds_read2_b32 v[8:9], v24 offset0:49 offset1:57
	ds_read2_b32 v[18:19], v24 offset0:16 offset1:24
	ds_read2_b32 v[26:27], v24 offset0:82 offset1:90
	ds_read2_b32 v[28:29], v24 offset0:115 offset1:123
	ds_read2_b32 v[30:31], v24 offset0:148 offset1:156
	ds_read2_b32 v[32:33], v24 offset0:181 offset1:189
	ds_read2_b32 v[34:35], v24 offset0:214 offset1:222
	ds_read2_b32 v[36:37], v24 offset0:247 offset1:255
	v_lshlrev_b64 v[40:41], 11, v[40:41]
	s_waitcnt lgkmcnt(6)
	v_cvt_pk_bf16_f32 v14, v18, v8
	s_waitcnt lgkmcnt(4)
	v_cvt_pk_bf16_f32 v15, v26, v28
	s_waitcnt lgkmcnt(2)
	v_cvt_pk_bf16_f32 v16, v30, v32
	s_waitcnt lgkmcnt(0)
	v_cvt_pk_bf16_f32 v17, v34, v36
	v_lshl_add_u64 v[40:41], v[6:7], 0, v[40:41]
	v_add_u32_e32 v8, 24, v38
	global_store_dwordx4 v[40:41], v[14:17], off
	s_nop 1
	v_cvt_pk_bf16_f32 v14, v19, v9
	v_ashrrev_i32_e32 v9, 31, v8
	v_lshlrev_b64 v[8:9], 11, v[8:9]
	v_cvt_pk_bf16_f32 v15, v27, v29
	v_cvt_pk_bf16_f32 v16, v31, v33
	v_cvt_pk_bf16_f32 v17, v35, v37
	v_lshl_add_u64 v[6:7], v[6:7], 0, v[8:9]
	global_store_dwordx4 v[6:7], v[14:17], off
	s_waitcnt lgkmcnt(0)
	s_cbranch_execnz .LBB0_1131
	s_branch .LBB0_1130

.LBB0_1139:
	s_mul_hi_i32 s10, s9, 0x2aaaaaab
	s_lshr_b32 s11, s10, 31
	s_ashr_i32 s10, s10, 4
	s_add_i32 s10, s10, s11
	s_lshl_b32 s14, s10, 6
	s_andn2_b64 vcc, exec, s[6:7]
	s_mulk_i32 s10, 0xf400
	s_cbranch_vccnz .LBB0_1141
	s_add_i32 s18, s8, s10
	v_or_b32_e32 v0, s14, v20
	s_ashr_i32 s19, s18, 31
	v_lshl_add_u64 v[18:19], s[18:19], 2, v[2:3]
	s_movk_i32 s11, 0x3000
	v_or_b32_e32 v11, 8, v0
	v_mad_i64_i32 v[6:7], s[12:13], v0, s11, v[18:19]
	v_mad_i64_i32 v[14:15], s[12:13], v11, s11, v[18:19]
	v_or_b32_e32 v11, 16, v0
	global_load_dwordx4 v[6:9], v[6:7], off nt
	v_mad_i64_i32 v[26:27], s[12:13], v11, s11, v[18:19]
	global_load_dwordx4 v[14:17], v[14:15], off nt
	v_or_b32_e32 v11, 24, v0
	global_load_dwordx4 v[26:29], v[26:27], off nt
	v_mad_i64_i32 v[30:31], s[12:13], v11, s11, v[18:19]
	v_or_b32_e32 v11, 32, v0
	global_load_dwordx4 v[30:33], v[30:31], off nt
	v_mad_i64_i32 v[34:35], s[12:13], v11, s11, v[18:19]
	global_load_dwordx4 v[34:37], v[34:35], off nt
	v_or_b32_e32 v11, 40, v0
	v_mad_i64_i32 v[38:39], s[12:13], v11, s11, v[18:19]
	global_load_dwordx4 v[38:41], v[38:39], off nt
	v_or_b32_e32 v11, 48, v0
	v_mad_i64_i32 v[42:43], s[12:13], v11, s11, v[18:19]
	global_load_dwordx4 v[42:45], v[42:43], off nt
	v_or_b32_e32 v0, 56, v0
	v_mad_i64_i32 v[18:19], s[12:13], v0, s11, v[18:19]
	global_load_dwordx4 v[46:49], v[18:19], off nt
	v_add_u32_e32 v0, v21, v23
	s_ashr_i32 s15, s14, 31
	s_waitcnt vmcnt(7)
	ds_write2_b32 v22, v6, v7 offset1:1
	ds_write2_b32 v22, v8, v9 offset0:2 offset1:3
	v_add_u32_e32 v6, 0x420, v0
	s_waitcnt vmcnt(6)
	ds_write2_b32 v0, v14, v15 offset1:1
	ds_write2_b32 v0, v16, v17 offset0:2 offset1:3
	v_add_u32_e32 v8, s18, v20
	s_waitcnt vmcnt(5)
	ds_write2_b32 v6, v26, v27 offset1:1
	v_add_u32_e32 v6, 0x428, v0
	ds_write2_b32 v6, v28, v29 offset1:1
	v_add_u32_e32 v6, 0x840, v0
	v_add_u32_e32 v0, 0x848, v0
	s_waitcnt vmcnt(4)
	ds_write2_b32 v0, v32, v33 offset1:1
	v_add_u32_e32 v0, 0x1080, v22
	s_waitcnt vmcnt(3)
	ds_write2_b32 v0, v34, v35 offset1:1
	v_add_u32_e32 v0, 0x1088, v22
	ds_write2_b32 v0, v36, v37 offset1:1
	v_add_u32_e32 v0, 0x14a0, v22
	s_waitcnt vmcnt(2)
	ds_write2_b32 v0, v38, v39 offset1:1
	v_add_u32_e32 v0, 0x14a8, v22
	ds_write2_b32 v0, v40, v41 offset1:1
	v_add_u32_e32 v0, 0x18c0, v22
	s_waitcnt vmcnt(1)
	ds_write2_b32 v0, v42, v43 offset1:1
	v_add_u32_e32 v0, 0x18c8, v22
	ds_write2_b32 v0, v44, v45 offset1:1
	v_add_u32_e32 v0, 0x1ce0, v22
	s_waitcnt vmcnt(0)
	ds_write2_b32 v0, v46, v47 offset1:1
	v_add_u32_e32 v0, 0x1ce8, v22
	ds_write2_b32 v6, v30, v31 offset1:1
	ds_write2_b32 v0, v48, v49 offset1:1
	s_waitcnt lgkmcnt(0)
	ds_read2_b32 v[18:19], v24 offset0:33 offset1:41
	ds_read2_b32 v[26:27], v24 offset1:8
	ds_read2_b32 v[28:29], v24 offset0:66 offset1:74
	ds_read2_b32 v[30:31], v24 offset0:99 offset1:107
	ds_read2_b32 v[32:33], v24 offset0:132 offset1:140
	ds_read2_b32 v[34:35], v24 offset0:165 offset1:173
	ds_read2_b32 v[36:37], v24 offset0:198 offset1:206
	ds_read2_b32 v[38:39], v24 offset0:231 offset1:239
	v_ashrrev_i32_e32 v9, 31, v8
	v_lshl_add_u64 v[6:7], s[14:15], 1, v[4:5]
	v_lshlrev_b64 v[40:41], 11, v[8:9]
	s_waitcnt lgkmcnt(6)
	v_cvt_pk_bf16_f32 v14, v26, v18
	s_waitcnt lgkmcnt(4)
	v_cvt_pk_bf16_f32 v15, v28, v30
	s_waitcnt lgkmcnt(2)
	v_cvt_pk_bf16_f32 v16, v32, v34
	s_waitcnt lgkmcnt(0)
	v_cvt_pk_bf16_f32 v17, v36, v38
	v_lshl_add_u64 v[40:41], v[6:7], 0, v[40:41]
	v_add_u32_e32 v18, 8, v8
	global_store_dwordx4 v[40:41], v[14:17], off
	v_add_u32_e32 v40, 16, v8
	v_ashrrev_i32_e32 v41, 31, v40
	v_cvt_pk_bf16_f32 v14, v27, v19
	v_ashrrev_i32_e32 v19, 31, v18
	v_lshlrev_b64 v[18:19], 11, v[18:19]
	v_cvt_pk_bf16_f32 v15, v29, v31
	v_cvt_pk_bf16_f32 v16, v33, v35
	v_cvt_pk_bf16_f32 v17, v37, v39
	v_lshl_add_u64 v[18:19], v[6:7], 0, v[18:19]
	global_store_dwordx4 v[18:19], v[14:17], off
	ds_read2_b32 v[18:19], v24 offset0:49 offset1:57
	ds_read2_b32 v[26:27], v24 offset0:16 offset1:24
	ds_read2_b32 v[28:29], v24 offset0:82 offset1:90
	ds_read2_b32 v[30:31], v24 offset0:115 offset1:123
	ds_read2_b32 v[32:33], v24 offset0:148 offset1:156
	ds_read2_b32 v[34:35], v24 offset0:181 offset1:189
	ds_read2_b32 v[36:37], v24 offset0:214 offset1:222
	ds_read2_b32 v[38:39], v24 offset0:247 offset1:255
	v_add_u32_e32 v8, 24, v8
	v_lshlrev_b64 v[40:41], 11, v[40:41]
	v_ashrrev_i32_e32 v9, 31, v8
	s_waitcnt lgkmcnt(6)
	v_cvt_pk_bf16_f32 v14, v26, v18
	s_waitcnt lgkmcnt(4)
	v_cvt_pk_bf16_f32 v15, v28, v30
	s_waitcnt lgkmcnt(2)
	v_cvt_pk_bf16_f32 v16, v32, v34
	s_waitcnt lgkmcnt(0)
	v_cvt_pk_bf16_f32 v17, v36, v38
	v_lshl_add_u64 v[40:41], v[6:7], 0, v[40:41]
	v_lshlrev_b64 v[8:9], 11, v[8:9]
	global_store_dwordx4 v[40:41], v[14:17], off
	v_lshl_add_u64 v[6:7], v[6:7], 0, v[8:9]
	s_nop 0
	v_cvt_pk_bf16_f32 v14, v27, v19
	v_cvt_pk_bf16_f32 v15, v29, v31
	v_cvt_pk_bf16_f32 v16, v33, v35
	v_cvt_pk_bf16_f32 v17, v37, v39
	global_store_dwordx4 v[6:7], v[14:17], off
	s_waitcnt lgkmcnt(0)
	s_cbranch_execnz .LBB0_1138
	s_branch .LBB0_1137

.LBB0_1145:
	s_ashr_i32 s9, s8, 31
	s_lshr_b32 s9, s9, 27
	s_add_i32 s9, s8, s9
	s_ashr_i32 s9, s9, 5
	s_lshl_b32 s14, s9, 6
	s_lshl_b32 s9, s9, 10
	s_andn2_b64 vcc, exec, s[6:7]
	s_sub_i32 s9, 0, s9
	s_cbranch_vccnz .LBB0_1147
	s_add_i32 s18, s5, s9
	v_or_b32_e32 v18, s14, v20
	s_ashr_i32 s19, s18, 31
	v_ashrrev_i32_e32 v19, 31, v18
	v_or_b32_e32 v14, 8, v18
	v_or_b32_e32 v26, 16, v18
	v_lshl_add_u64 v[46:47], s[18:19], 2, v[2:3]
	v_lshlrev_b64 v[6:7], 12, v[18:19]
	v_ashrrev_i32_e32 v15, 31, v14
	v_ashrrev_i32_e32 v27, 31, v26
	v_lshl_add_u64 v[6:7], v[46:47], 0, v[6:7]
	v_lshlrev_b64 v[14:15], 12, v[14:15]
	v_lshlrev_b64 v[26:27], 12, v[26:27]
	v_or_b32_e32 v30, 24, v18
	global_load_dwordx4 v[6:9], v[6:7], off nt
	v_lshl_add_u64 v[14:15], v[46:47], 0, v[14:15]
	v_lshl_add_u64 v[26:27], v[46:47], 0, v[26:27]
	v_ashrrev_i32_e32 v31, 31, v30
	v_or_b32_e32 v34, 32, v18
	global_load_dwordx4 v[14:17], v[14:15], off nt
	v_lshlrev_b64 v[30:31], 12, v[30:31]
	global_load_dwordx4 v[26:29], v[26:27], off nt
	v_ashrrev_i32_e32 v35, 31, v34
	v_lshl_add_u64 v[30:31], v[46:47], 0, v[30:31]
	v_lshlrev_b64 v[34:35], 12, v[34:35]
	v_or_b32_e32 v38, 40, v18
	global_load_dwordx4 v[30:33], v[30:31], off nt
	v_lshl_add_u64 v[34:35], v[46:47], 0, v[34:35]
	v_ashrrev_i32_e32 v39, 31, v38
	global_load_dwordx4 v[34:37], v[34:35], off nt
	v_lshlrev_b64 v[38:39], 12, v[38:39]
	v_or_b32_e32 v42, 48, v18
	v_lshl_add_u64 v[38:39], v[46:47], 0, v[38:39]
	v_ashrrev_i32_e32 v43, 31, v42
	global_load_dwordx4 v[38:41], v[38:39], off nt
	v_lshlrev_b64 v[42:43], 12, v[42:43]
	v_or_b32_e32 v18, 56, v18
	v_lshl_add_u64 v[42:43], v[46:47], 0, v[42:43]
	v_ashrrev_i32_e32 v19, 31, v18
	global_load_dwordx4 v[42:45], v[42:43], off nt
	v_lshlrev_b64 v[18:19], 12, v[18:19]
	v_lshl_add_u64 v[18:19], v[46:47], 0, v[18:19]
	global_load_dwordx4 v[46:49], v[18:19], off nt
	v_add_u32_e32 v0, v21, v23
	s_ashr_i32 s15, s14, 31
	s_waitcnt vmcnt(7)
	ds_write2_b32 v22, v6, v7 offset1:1
	ds_write2_b32 v22, v8, v9 offset0:2 offset1:3
	v_add_u32_e32 v6, 0x420, v0
	s_waitcnt vmcnt(6)
	ds_write2_b32 v0, v14, v15 offset1:1
	ds_write2_b32 v0, v16, v17 offset0:2 offset1:3
	s_waitcnt vmcnt(5)
	ds_write2_b32 v6, v26, v27 offset1:1
	v_add_u32_e32 v6, 0x428, v0
	ds_write2_b32 v6, v28, v29 offset1:1
	v_add_u32_e32 v6, 0x840, v0
	v_add_u32_e32 v0, 0x848, v0
	s_waitcnt vmcnt(4)
	ds_write2_b32 v0, v32, v33 offset1:1
	v_add_u32_e32 v0, 0x1080, v22
	ds_write2_b32 v6, v30, v31 offset1:1
	s_waitcnt vmcnt(3)
	ds_write2_b32 v0, v34, v35 offset1:1
	v_add_u32_e32 v0, 0x1088, v22
	ds_write2_b32 v0, v36, v37 offset1:1
	v_add_u32_e32 v0, 0x14a0, v22
	v_lshl_add_u64 v[6:7], s[14:15], 1, v[4:5]
	s_waitcnt vmcnt(2)
	ds_write2_b32 v0, v38, v39 offset1:1
	v_add_u32_e32 v0, 0x14a8, v22
	ds_write2_b32 v0, v40, v41 offset1:1
	v_add_u32_e32 v0, 0x18c0, v22
	v_add_u32_e32 v38, s18, v20
	s_waitcnt vmcnt(1)
	ds_write2_b32 v0, v42, v43 offset1:1
	v_add_u32_e32 v0, 0x18c8, v22
	ds_write2_b32 v0, v44, v45 offset1:1
	v_add_u32_e32 v0, 0x1ce0, v22
	s_waitcnt vmcnt(0)
	ds_write2_b32 v0, v46, v47 offset1:1
	v_add_u32_e32 v0, 0x1ce8, v22
	ds_write2_b32 v0, v48, v49 offset1:1
	s_waitcnt lgkmcnt(0)
	ds_read2_b32 v[8:9], v24 offset0:33 offset1:41
	ds_read2_b32 v[18:19], v24 offset1:8
	ds_read2_b32 v[26:27], v24 offset0:66 offset1:74
	ds_read2_b32 v[28:29], v24 offset0:99 offset1:107
	ds_read2_b32 v[30:31], v24 offset0:132 offset1:140
	ds_read2_b32 v[32:33], v24 offset0:165 offset1:173
	ds_read2_b32 v[34:35], v24 offset0:198 offset1:206
	ds_read2_b32 v[36:37], v24 offset0:231 offset1:239
	v_ashrrev_i32_e32 v39, 31, v38
	v_lshlrev_b64 v[40:41], 11, v[38:39]
	s_waitcnt lgkmcnt(6)
	v_cvt_pk_bf16_f32 v14, v18, v8
	s_waitcnt lgkmcnt(4)
	v_cvt_pk_bf16_f32 v15, v26, v28
	s_waitcnt lgkmcnt(2)
	v_cvt_pk_bf16_f32 v16, v30, v32
	s_waitcnt lgkmcnt(0)
	v_cvt_pk_bf16_f32 v17, v34, v36
	v_lshl_add_u64 v[40:41], v[6:7], 0, v[40:41]
	v_add_u32_e32 v8, 8, v38
	global_store_dwordx4 v[40:41], v[14:17], off
	v_add_u32_e32 v40, 16, v38
	v_ashrrev_i32_e32 v41, 31, v40
	v_cvt_pk_bf16_f32 v14, v19, v9
	v_ashrrev_i32_e32 v9, 31, v8
	v_lshlrev_b64 v[8:9], 11, v[8:9]
	v_cvt_pk_bf16_f32 v15, v27, v29
	v_cvt_pk_bf16_f32 v16, v31, v33
	v_cvt_pk_bf16_f32 v17, v35, v37
	v_lshl_add_u64 v[8:9], v[6:7], 0, v[8:9]
	global_store_dwordx4 v[8:9], v[14:17], off
	ds_read2_b32 v[8:9], v24 offset0:49 offset1:57
	ds_read2_b32 v[18:19], v24 offset0:16 offset1:24
	ds_read2_b32 v[26:27], v24 offset0:82 offset1:90
	ds_read2_b32 v[28:29], v24 offset0:115 offset1:123
	ds_read2_b32 v[30:31], v24 offset0:148 offset1:156
	ds_read2_b32 v[32:33], v24 offset0:181 offset1:189
	ds_read2_b32 v[34:35], v24 offset0:214 offset1:222
	ds_read2_b32 v[36:37], v24 offset0:247 offset1:255
	v_lshlrev_b64 v[40:41], 11, v[40:41]
	s_waitcnt lgkmcnt(6)
	v_cvt_pk_bf16_f32 v14, v18, v8
	s_waitcnt lgkmcnt(4)
	v_cvt_pk_bf16_f32 v15, v26, v28
	s_waitcnt lgkmcnt(2)
	v_cvt_pk_bf16_f32 v16, v30, v32
	s_waitcnt lgkmcnt(0)
	v_cvt_pk_bf16_f32 v17, v34, v36
	v_lshl_add_u64 v[40:41], v[6:7], 0, v[40:41]
	v_add_u32_e32 v8, 24, v38
	global_store_dwordx4 v[40:41], v[14:17], off
	s_nop 1
	v_cvt_pk_bf16_f32 v14, v19, v9
	v_ashrrev_i32_e32 v9, 31, v8
	v_lshlrev_b64 v[8:9], 11, v[8:9]
	v_cvt_pk_bf16_f32 v15, v27, v29
	v_cvt_pk_bf16_f32 v16, v31, v33
	v_cvt_pk_bf16_f32 v17, v35, v37
	v_lshl_add_u64 v[6:7], v[6:7], 0, v[8:9]
	global_store_dwordx4 v[6:7], v[14:17], off
	s_waitcnt lgkmcnt(0)
	s_cbranch_execnz .LBB0_1144
	s_branch .LBB0_1143

.LBB0_1153:
	s_ashr_i32 s6, s3, 31
	s_lshr_b32 s6, s6, 25
	s_add_i32 s6, s3, s6
	s_ashr_i32 s7, s6, 7
	s_lshl_b32 s6, s7, 6
	s_lshl_b32 s7, s7, 12
	s_andn2_b64 vcc, exec, s[0:1]
	s_sub_i32 s8, 0, s7
	s_cbranch_vccnz .LBB0_1155
	s_add_i32 s14, s5, s8
	v_or_b32_e32 v18, s6, v20
	s_ashr_i32 s15, s14, 31
	v_ashrrev_i32_e32 v19, 31, v18
	v_or_b32_e32 v10, 8, v18
	v_or_b32_e32 v14, 16, v18
	v_lshl_add_u64 v[42:43], s[14:15], 2, v[2:3]
	v_lshlrev_b64 v[6:7], 14, v[18:19]
	v_ashrrev_i32_e32 v11, 31, v10
	v_ashrrev_i32_e32 v15, 31, v14
	v_lshl_add_u64 v[6:7], v[42:43], 0, v[6:7]
	v_lshlrev_b64 v[10:11], 14, v[10:11]
	v_lshlrev_b64 v[14:15], 14, v[14:15]
	v_or_b32_e32 v26, 24, v18
	global_load_dwordx4 v[6:9], v[6:7], off nt
	v_lshl_add_u64 v[10:11], v[42:43], 0, v[10:11]
	v_lshl_add_u64 v[14:15], v[42:43], 0, v[14:15]
	v_ashrrev_i32_e32 v27, 31, v26
	v_or_b32_e32 v30, 32, v18
	global_load_dwordx4 v[10:13], v[10:11], off nt
	v_lshlrev_b64 v[26:27], 14, v[26:27]
	global_load_dwordx4 v[14:17], v[14:15], off nt
	v_ashrrev_i32_e32 v31, 31, v30
	v_lshl_add_u64 v[26:27], v[42:43], 0, v[26:27]
	v_lshlrev_b64 v[30:31], 14, v[30:31]
	v_or_b32_e32 v34, 40, v18
	global_load_dwordx4 v[26:29], v[26:27], off nt
	v_lshl_add_u64 v[30:31], v[42:43], 0, v[30:31]
	v_ashrrev_i32_e32 v35, 31, v34
	global_load_dwordx4 v[30:33], v[30:31], off nt
	v_lshlrev_b64 v[34:35], 14, v[34:35]
	v_or_b32_e32 v38, 48, v18
	v_lshl_add_u64 v[34:35], v[42:43], 0, v[34:35]
	v_ashrrev_i32_e32 v39, 31, v38
	global_load_dwordx4 v[34:37], v[34:35], off nt
	v_lshlrev_b64 v[38:39], 14, v[38:39]
	v_or_b32_e32 v18, 56, v18
	v_lshl_add_u64 v[38:39], v[42:43], 0, v[38:39]
	v_ashrrev_i32_e32 v19, 31, v18
	global_load_dwordx4 v[38:41], v[38:39], off nt
	v_lshlrev_b64 v[18:19], 14, v[18:19]
	v_lshl_add_u64 v[18:19], v[42:43], 0, v[18:19]
	global_load_dwordx4 v[42:45], v[18:19], off nt
	v_add_u32_e32 v0, v21, v23
	s_ashr_i32 s7, s6, 31
	s_waitcnt vmcnt(7)
	ds_write2_b32 v22, v6, v7 offset1:1
	ds_write2_b32 v22, v8, v9 offset0:2 offset1:3
	v_add_u32_e32 v6, 0x420, v0
	s_waitcnt vmcnt(6)
	ds_write2_b32 v0, v10, v11 offset1:1
	ds_write2_b32 v0, v12, v13 offset0:2 offset1:3
	s_waitcnt vmcnt(5)
	ds_write2_b32 v6, v14, v15 offset1:1
	v_add_u32_e32 v6, 0x428, v0
	ds_write2_b32 v6, v16, v17 offset1:1
	v_add_u32_e32 v6, 0x840, v0
	v_add_u32_e32 v0, 0x848, v0
	s_waitcnt vmcnt(4)
	ds_write2_b32 v0, v28, v29 offset1:1
	v_add_u32_e32 v0, 0x1080, v22
	ds_write2_b32 v6, v26, v27 offset1:1
	s_waitcnt vmcnt(3)
	ds_write2_b32 v0, v30, v31 offset1:1
	v_add_u32_e32 v0, 0x1088, v22
	ds_write2_b32 v0, v32, v33 offset1:1
	v_add_u32_e32 v0, 0x14a0, v22
	v_lshl_add_u64 v[6:7], s[6:7], 1, v[4:5]
	s_waitcnt vmcnt(2)
	ds_write2_b32 v0, v34, v35 offset1:1
	v_add_u32_e32 v0, 0x14a8, v22
	ds_write2_b32 v0, v36, v37 offset1:1
	v_add_u32_e32 v0, 0x18c0, v22
	v_add_u32_e32 v34, s14, v20
	s_waitcnt vmcnt(1)
	ds_write2_b32 v0, v38, v39 offset1:1
	v_add_u32_e32 v0, 0x18c8, v22
	ds_write2_b32 v0, v40, v41 offset1:1
	v_add_u32_e32 v0, 0x1ce0, v22
	s_waitcnt vmcnt(0)
	ds_write2_b32 v0, v42, v43 offset1:1
	v_add_u32_e32 v0, 0x1ce8, v22
	ds_write2_b32 v0, v44, v45 offset1:1
	s_waitcnt lgkmcnt(0)
	ds_read2_b32 v[12:13], v24 offset0:33 offset1:41
	ds_read2_b32 v[14:15], v24 offset1:8
	ds_read2_b32 v[16:17], v24 offset0:66 offset1:74
	ds_read2_b32 v[18:19], v24 offset0:99 offset1:107
	ds_read2_b32 v[26:27], v24 offset0:132 offset1:140
	ds_read2_b32 v[28:29], v24 offset0:165 offset1:173
	ds_read2_b32 v[30:31], v24 offset0:198 offset1:206
	ds_read2_b32 v[32:33], v24 offset0:231 offset1:239
	v_ashrrev_i32_e32 v35, 31, v34
	v_lshlrev_b64 v[36:37], 11, v[34:35]
	s_waitcnt lgkmcnt(6)
	v_cvt_pk_bf16_f32 v8, v14, v12
	s_waitcnt lgkmcnt(4)
	v_cvt_pk_bf16_f32 v9, v16, v18
	s_waitcnt lgkmcnt(2)
	v_cvt_pk_bf16_f32 v10, v26, v28
	s_waitcnt lgkmcnt(0)
	v_cvt_pk_bf16_f32 v11, v30, v32
	v_lshl_add_u64 v[36:37], v[6:7], 0, v[36:37]
	v_add_u32_e32 v12, 8, v34
	global_store_dwordx4 v[36:37], v[8:11], off
	v_add_u32_e32 v36, 16, v34
	v_ashrrev_i32_e32 v37, 31, v36
	v_cvt_pk_bf16_f32 v8, v15, v13
	v_ashrrev_i32_e32 v13, 31, v12
	v_lshlrev_b64 v[12:13], 11, v[12:13]
	v_cvt_pk_bf16_f32 v9, v17, v19
	v_cvt_pk_bf16_f32 v10, v27, v29
	v_cvt_pk_bf16_f32 v11, v31, v33
	v_lshl_add_u64 v[12:13], v[6:7], 0, v[12:13]
	global_store_dwordx4 v[12:13], v[8:11], off
	ds_read2_b32 v[12:13], v24 offset0:49 offset1:57
	ds_read2_b32 v[14:15], v24 offset0:16 offset1:24
	ds_read2_b32 v[16:17], v24 offset0:82 offset1:90
	ds_read2_b32 v[18:19], v24 offset0:115 offset1:123
	ds_read2_b32 v[26:27], v24 offset0:148 offset1:156
	ds_read2_b32 v[28:29], v24 offset0:181 offset1:189
	ds_read2_b32 v[30:31], v24 offset0:214 offset1:222
	ds_read2_b32 v[32:33], v24 offset0:247 offset1:255
	v_lshlrev_b64 v[36:37], 11, v[36:37]
	s_waitcnt lgkmcnt(6)
	v_cvt_pk_bf16_f32 v8, v14, v12
	s_waitcnt lgkmcnt(4)
	v_cvt_pk_bf16_f32 v9, v16, v18
	s_waitcnt lgkmcnt(2)
	v_cvt_pk_bf16_f32 v10, v26, v28
	s_waitcnt lgkmcnt(0)
	v_cvt_pk_bf16_f32 v11, v30, v32
	v_lshl_add_u64 v[36:37], v[6:7], 0, v[36:37]
	v_add_u32_e32 v12, 24, v34
	global_store_dwordx4 v[36:37], v[8:11], off
	s_nop 1
	v_cvt_pk_bf16_f32 v8, v15, v13
	v_ashrrev_i32_e32 v13, 31, v12
	v_lshlrev_b64 v[12:13], 11, v[12:13]
	v_cvt_pk_bf16_f32 v9, v17, v19
	v_cvt_pk_bf16_f32 v10, v27, v29
	v_cvt_pk_bf16_f32 v11, v31, v33
	v_lshl_add_u64 v[6:7], v[6:7], 0, v[12:13]
	global_store_dwordx4 v[6:7], v[8:11], off
	s_waitcnt lgkmcnt(0)
	s_cbranch_execnz .LBB0_1152
	s_branch .LBB0_1151
